# P3 second unit: residual streamed during its K-loop (2 global_load_dwordx4 per iteration into staging quads, pk_add into accumulators one iteration later; loop copy with vmcnt adjusted), epilogue stor
# speedup vs baseline: 1.0212x; 1.0073x over previous
;     __host__ __device__ bool next(int i, Unit& u) const { if (lo + i >= hi) return false; return base.next(lo + i, u); }
; #define PG8_STAGE(bufoff, gbase, voff) do { _Pragma("unroll") for (int _i = 0; _i < 2; ++_i) \
;         __builtin_amdgcn_global_load_lds((const unsigned*)((const char*)(gbase) + (voff)[_i]), (PG8_LAS unsigned*)(lds + (bufoff) + ldsw + _i * 8192), 16, 0, 0); } while (0)
; #define PG8_LDA(dst, b, h) do { _Pragma("unroll") for (int m = 0; m < 4; ++m) _Pragma("unroll") for (int k = 0; k < 2; ++k) dst[m][k] = *(const PG8_LAS bf16x8*)(lds + PG8_SA(b, h) + aoff + m * 2048 + k * 1024); } while (0)
; #define PG8_LDB(dst, b, h) do { _Pragma("unroll") for (int n = 0; n < 2; ++n) _Pragma("unroll") for (int k = 0; k < 2; ++k) dst[n][k] = *(const PG8_LAS bf16x8*)(lds + PG8_SB(b, h) + boff + n * 2048 + k * 1024); } while (0)
; #define PG8_WAIT_V(n) asm volatile("s_waitcnt vmcnt(" #n ")" ::: "memory")
; template <class Epi, class Sched, bool ALIGN_EPI = false, bool SP2 = false>
; __device__ __forceinline__ void gemm_phase(PG8_LAS unsigned char* lds, const Gemm g, const Sched& S, const Epi& E) {
;     ...
;         const bool has_next = S.next(ui + 1, nxt);
;         const char* nA = has_next ? (const char*)g.A + (size_t)nxt.pm * tstep : cA; const char* nB = has_next ? (const char*)g.Bt + (size_t)nxt.pn * tstep : cB;
;         for (int t = 0; t < nt; t += 2) {
;             const bool last = (t == nt - 2);
;             const char* a1 = cA + (size_t)(t + 1) * kstep;
;             const char* a2 = last ? nA : cA + (size_t)(t + 2) * kstep; const char* b2 = last ? nB : cB + (size_t)(t + 2) * kstep;
;             const char* a3 = a2 + kstep; const char* b3 = b2 + kstep;
;             if (last && has_next) S.a_ready(nxt);
;             if constexpr (SP2) {
;             PG8_LDB(B0, 0, 0); PG8_LDB(B1, 0, 1); PG8_SCHED; PG8_LDA(At, 0, 0); PG8_STAGE(PG8_SA(1, 1), a1 + hstep, voffA);
;             PG8_WAIT_V(8); PG8_WAIT_L(0); PG8_BAR; PG8_MMA(0, 0, At, B0); PG8_MMA(0, 1, At, B1); PG8_BAR; PG8_SCHED;
;     ...
; #pragma unroll
;         for (int a = 0; a < 2; ++a)
; #pragma unroll
;             for (int b = 0; b < 2; ++b)
; #pragma unroll
;                 for (int m = 0; m < 4; ++m)
; #pragma unroll
;                     for (int n = 0; n < 2; ++n) acc[a][b][m][n] = (f32x4){0.f, 0.f, 0.f, 0.f};
;         cur = nxt; cA = nA; cB = nB; ++ui;
.LBB0_457:
	s_ashr_i32 s19, s18, 31
	s_lshl_b64 s[20:21], s[18:19], 20
	s_add_u32 s20, s80, s20
	s_addc_u32 s21, s81, s21
	s_and_b64 s[22:23], s[0:1], exec
	s_cselect_b32 s19, s21, s27
	s_cselect_b32 s31, s20, s26
	s_ashr_i32 s17, s16, 31
	s_lshl_b64 s[22:23], s[16:17], 20
	s_add_u32 s22, s72, s22
	s_addc_u32 s23, s73, s23
	s_and_b64 s[34:35], s[0:1], exec
	s_cselect_b32 s17, s23, s29
	s_cselect_b32 s46, s22, s28
	s_add_u32 s26, s26, 0x80080
	s_addc_u32 s27, s27, 0
	s_add_u32 s47, s28, 0x100
	s_addc_u32 s48, s29, 0
	s_mov_b32 s49, -2
	s_cmp_eq_u32 s101, 1
	s_cbranch_scc1 .Lp3_preloaded
	v_mov_b32_e32 v0, 0
	v_mov_b32_e32 v1, v0
	v_mov_b32_e32 v2, v0
	v_mov_b32_e32 v3, v0
	v_mov_b32_e32 v4, v0
	v_mov_b32_e32 v5, v0
	v_mov_b32_e32 v6, v0
	v_mov_b32_e32 v7, v0
	v_mov_b32_e32 v8, v0
	v_mov_b32_e32 v9, v0
	v_mov_b32_e32 v10, v0
	v_mov_b32_e32 v11, v0
	v_mov_b32_e32 v12, v0
	v_mov_b32_e32 v13, v0
	v_mov_b32_e32 v14, v0
	v_mov_b32_e32 v15, v0
	v_mov_b32_e32 v20, v0
	v_mov_b32_e32 v21, v0
	v_mov_b32_e32 v22, v0
	v_mov_b32_e32 v23, v0
	v_mov_b32_e32 v24, v0
	v_mov_b32_e32 v25, v0
	v_mov_b32_e32 v26, v0
	v_mov_b32_e32 v27, v0
	v_mov_b32_e32 v32, v0
	v_mov_b32_e32 v33, v0
	v_mov_b32_e32 v34, v0
	v_mov_b32_e32 v35, v0
	v_mov_b32_e32 v40, v0
	v_mov_b32_e32 v41, v0
	v_mov_b32_e32 v42, v0
	v_mov_b32_e32 v43, v0
	v_mov_b32_e32 v16, v0
	v_mov_b32_e32 v17, v0
	v_mov_b32_e32 v18, v0
	v_mov_b32_e32 v19, v0
	v_mov_b32_e32 v28, v0
	v_mov_b32_e32 v29, v0
	v_mov_b32_e32 v30, v0
	v_mov_b32_e32 v31, v0
	v_mov_b32_e32 v36, v0
	v_mov_b32_e32 v37, v0
	v_mov_b32_e32 v38, v0
	v_mov_b32_e32 v39, v0
	v_mov_b32_e32 v44, v0
	v_mov_b32_e32 v45, v0
	v_mov_b32_e32 v46, v0
	v_mov_b32_e32 v47, v0
	v_mov_b32_e32 v48, v0
	v_mov_b32_e32 v49, v0
	v_mov_b32_e32 v50, v0
	v_mov_b32_e32 v51, v0
	v_mov_b32_e32 v52, v0
	v_mov_b32_e32 v53, v0
	v_mov_b32_e32 v54, v0
	v_mov_b32_e32 v55, v0
	v_mov_b32_e32 v56, v0
	v_mov_b32_e32 v57, v0
	v_mov_b32_e32 v58, v0
	v_mov_b32_e32 v59, v0
	v_mov_b32_e32 v60, v0
	v_mov_b32_e32 v61, v0
	v_mov_b32_e32 v62, v0
	v_mov_b32_e32 v63, v0
	v_mov_b32_e32 v64, v0
	v_mov_b32_e32 v65, v0
	v_mov_b32_e32 v66, v0
	v_mov_b32_e32 v67, v0
	v_mov_b32_e32 v68, v0
	v_mov_b32_e32 v69, v0
	v_mov_b32_e32 v70, v0
	v_mov_b32_e32 v71, v0
	v_mov_b32_e32 v72, v0
	v_mov_b32_e32 v73, v0
	v_mov_b32_e32 v74, v0
	v_mov_b32_e32 v75, v0
	v_mov_b32_e32 v76, v0
	v_mov_b32_e32 v77, v0
	v_mov_b32_e32 v78, v0
	v_mov_b32_e32 v79, v0
	v_mov_b32_e32 v84, v0
	v_mov_b32_e32 v85, v0
	v_mov_b32_e32 v86, v0
	v_mov_b32_e32 v87, v0
	v_mov_b32_e32 v88, v0
	v_mov_b32_e32 v89, v0
	v_mov_b32_e32 v90, v0
	v_mov_b32_e32 v91, v0
	v_mov_b32_e32 v96, v0
	v_mov_b32_e32 v97, v0
	v_mov_b32_e32 v98, v0
	v_mov_b32_e32 v99, v0
	v_mov_b32_e32 v104, v0
	v_mov_b32_e32 v105, v0
	v_mov_b32_e32 v106, v0
	v_mov_b32_e32 v107, v0
	v_mov_b32_e32 v80, v0
	v_mov_b32_e32 v81, v0
	v_mov_b32_e32 v82, v0
	v_mov_b32_e32 v83, v0
	v_mov_b32_e32 v92, v0
	v_mov_b32_e32 v93, v0
	v_mov_b32_e32 v94, v0
	v_mov_b32_e32 v95, v0
	v_mov_b32_e32 v100, v0
	v_mov_b32_e32 v101, v0
	v_mov_b32_e32 v102, v0
	v_mov_b32_e32 v103, v0
	v_mov_b32_e32 v108, v0
	v_mov_b32_e32 v109, v0
	v_mov_b32_e32 v110, v0
	v_mov_b32_e32 v111, v0
	v_mov_b32_e32 v112, v0
	v_mov_b32_e32 v113, v0
	v_mov_b32_e32 v114, v0
	v_mov_b32_e32 v115, v0
	v_mov_b32_e32 v116, v0
	v_mov_b32_e32 v117, v0
	v_mov_b32_e32 v118, v0
	v_mov_b32_e32 v119, v0
	v_mov_b32_e32 v120, v0
	v_mov_b32_e32 v121, v0
	v_mov_b32_e32 v122, v0
	v_mov_b32_e32 v123, v0
	v_mov_b32_e32 v124, v0
	v_mov_b32_e32 v125, v0
	v_mov_b32_e32 v126, v0
	v_mov_b32_e32 v127, v0
	s_branch .Lp3_k2_entry
.LBB0_458:
	ds_read_b128 v[140:143], v149
	ds_read_b128 v[152:155], v149 offset:1024
	ds_read_b128 v[156:159], v149 offset:2048
	ds_read_b128 v[160:163], v149 offset:3072
	ds_read_b128 v[164:167], v150
	ds_read_b128 v[168:171], v150 offset:1024
	ds_read_b128 v[172:175], v150 offset:2048
	ds_read_b128 v[176:179], v150 offset:3072
	s_add_u32 s28, s26, 0xfff80080
	s_addc_u32 s29, s27, -1
	s_cmp_eq_u32 s49, 28
	s_cselect_b32 s35, s19, s29
	s_cselect_b32 s34, s31, s28
	s_cselect_b32 s29, s17, s48
	s_cselect_b32 s28, s46, s47
	v_lshl_add_u64 v[144:145], s[26:27], 0, v[132:133]
	s_add_i32 m0, s25, 0xc000
	ds_read_b128 v[180:183], v151
	ds_read_b128 v[184:187], v151 offset:1024
	ds_read_b128 v[188:191], v151 offset:2048
	ds_read_b128 v[192:195], v151 offset:3072
	ds_read_b128 v[196:199], v151 offset:4096
	ds_read_b128 v[200:203], v151 offset:5120
	ds_read_b128 v[204:207], v151 offset:6144
	ds_read_b128 v[208:211], v151 offset:7168
	global_load_lds_dwordx4 v[144:145], off
	v_lshl_add_u64 v[144:145], s[26:27], 0, v[134:135]
	s_add_i32 m0, s25, 0xe000
	s_nop 0
	global_load_lds_dwordx4 v[144:145], off
	s_waitcnt vmcnt(8)
	s_waitcnt lgkmcnt(0)
	s_barrier
; #define PG8_STAGE(bufoff, gbase, voff) do { _Pragma("unroll") for (int _i = 0; _i < 2; ++_i) \
;         __builtin_amdgcn_global_load_lds((const unsigned*)((const char*)(gbase) + (voff)[_i]), (PG8_LAS unsigned*)(lds + (bufoff) + ldsw + _i * 8192), 16, 0, 0); } while (0)
; #define PG8_LDA(dst, b, h) do { _Pragma("unroll") for (int m = 0; m < 4; ++m) _Pragma("unroll") for (int k = 0; k < 2; ++k) dst[m][k] = *(const PG8_LAS bf16x8*)(lds + PG8_SA(b, h) + aoff + m * 2048 + k * 1024); } while (0)
; #define PG8_LDB(dst, b, h) do { _Pragma("unroll") for (int n = 0; n < 2; ++n) _Pragma("unroll") for (int k = 0; k < 2; ++k) dst[n][k] = *(const PG8_LAS bf16x8*)(lds + PG8_SB(b, h) + boff + n * 2048 + k * 1024); } while (0)
; #define PG8_MMA(ai, bj, At, Bt) do { __builtin_amdgcn_s_setprio(1); _Pragma("unroll") for (int m = 0; m < 4; ++m) _Pragma("unroll") for (int n = 0; n < 2; ++n) _Pragma("unroll") for (int k = 0; k < 2; ++k) \
;         acc[ai][bj][m][n] = __builtin_amdgcn_mfma_f32_16x16x32_bf16(Bt[n][k], At[m][k], acc[ai][bj][m][n], 0, 0, 0); __builtin_amdgcn_s_setprio(0); } while (0)
; #define PG8_WAIT_V(n) asm volatile("s_waitcnt vmcnt(" #n ")" ::: "memory")
; #define PG8_WAIT_L(n) asm volatile("s_waitcnt lgkmcnt(" #n ")" ::: "memory")
; #define PG8_BAR __builtin_amdgcn_s_barrier()
; #define PG8_SCHED __builtin_amdgcn_sched_barrier(0)
; template <class Epi, class Sched, bool ALIGN_EPI = false, bool SP2 = false>
; __device__ __forceinline__ void gemm_phase(PG8_LAS unsigned char* lds, const Gemm g, const Sched& S, const Epi& E) {
;     ...
;             PG8_LDB(B0, 0, 0); PG8_LDB(B1, 0, 1); PG8_SCHED; PG8_LDA(At, 0, 0); PG8_STAGE(PG8_SA(1, 1), a1 + hstep, voffA);
;             PG8_WAIT_V(8); PG8_WAIT_L(0); PG8_BAR; PG8_MMA(0, 0, At, B0); PG8_MMA(0, 1, At, B1); PG8_BAR; PG8_SCHED;
;             PG8_LDA(At, 0, 1); PG8_STAGE(PG8_SB(0, 0), b2, voffB); PG8_STAGE(PG8_SB(0, 1), b2 + hstep, voffB); PG8_STAGE(PG8_SA(0, 0), a2, voffA);
;             PG8_WAIT_V(8); PG8_WAIT_L(0); PG8_BAR; PG8_MMA(1, 0, At, B0); PG8_MMA(1, 1, At, B1); PG8_BAR; PG8_SCHED;
	s_setprio 1
	s_waitcnt lgkmcnt(0)
	v_mfma_f32_16x16x32_bf16 v[124:127], v[140:143], v[180:183], v[124:127]
	v_mfma_f32_16x16x32_bf16 v[124:127], v[152:155], v[184:187], v[124:127]
	v_mfma_f32_16x16x32_bf16 v[116:119], v[152:155], v[192:195], v[116:119]
	v_mfma_f32_16x16x32_bf16 v[116:119], v[140:143], v[188:191], v[116:119]
	v_mfma_f32_16x16x32_bf16 v[108:111], v[140:143], v[196:199], v[108:111]
	v_mfma_f32_16x16x32_bf16 v[108:111], v[152:155], v[200:203], v[108:111]
	v_mfma_f32_16x16x32_bf16 v[92:95], v[152:155], v[208:211], v[92:95]
	v_mfma_f32_16x16x32_bf16 v[92:95], v[140:143], v[204:207], v[92:95]
	v_mfma_f32_16x16x32_bf16 v[80:83], v[156:159], v[204:207], v[80:83]
	v_mfma_f32_16x16x32_bf16 v[80:83], v[160:163], v[208:211], v[80:83]
	v_mfma_f32_16x16x32_bf16 v[100:103], v[160:163], v[200:203], v[100:103]
	v_mfma_f32_16x16x32_bf16 v[100:103], v[156:159], v[196:199], v[100:103]
	v_mfma_f32_16x16x32_bf16 v[112:115], v[156:159], v[188:191], v[112:115]
	v_mfma_f32_16x16x32_bf16 v[112:115], v[160:163], v[192:195], v[112:115]
	v_mfma_f32_16x16x32_bf16 v[120:123], v[160:163], v[184:187], v[120:123]
	v_mfma_f32_16x16x32_bf16 v[120:123], v[156:159], v[180:183], v[120:123]
	s_setprio 0
	s_setprio 1
	v_mfma_f32_16x16x32_bf16 v[104:107], v[164:167], v[180:183], v[104:107]
	v_mfma_f32_16x16x32_bf16 v[104:107], v[168:171], v[184:187], v[104:107]
	v_mfma_f32_16x16x32_bf16 v[88:91], v[168:171], v[192:195], v[88:91]
	v_mfma_f32_16x16x32_bf16 v[88:91], v[164:167], v[188:191], v[88:91]
	v_mfma_f32_16x16x32_bf16 v[76:79], v[164:167], v[196:199], v[76:79]
	v_mfma_f32_16x16x32_bf16 v[76:79], v[168:171], v[200:203], v[76:79]
	v_mfma_f32_16x16x32_bf16 v[68:71], v[168:171], v[208:211], v[68:71]
	v_mfma_f32_16x16x32_bf16 v[68:71], v[164:167], v[204:207], v[68:71]
	v_mfma_f32_16x16x32_bf16 v[64:67], v[172:175], v[204:207], v[64:67]
	v_mfma_f32_16x16x32_bf16 v[64:67], v[176:179], v[208:211], v[64:67]
	v_mfma_f32_16x16x32_bf16 v[72:75], v[176:179], v[200:203], v[72:75]
	v_mfma_f32_16x16x32_bf16 v[72:75], v[172:175], v[196:199], v[72:75]
	v_mfma_f32_16x16x32_bf16 v[84:87], v[172:175], v[188:191], v[84:87]
	v_mfma_f32_16x16x32_bf16 v[84:87], v[176:179], v[192:195], v[84:87]
	v_mfma_f32_16x16x32_bf16 v[96:99], v[176:179], v[184:187], v[96:99]
	v_mfma_f32_16x16x32_bf16 v[96:99], v[172:175], v[180:183], v[96:99]
	s_setprio 0
	s_barrier
	s_add_i32 s50, s43, s30
	v_lshl_add_u64 v[144:145], s[28:29], 0, v[128:129]
	s_mov_b32 m0, s50
	ds_read_b128 v[180:183], v151 offset:16384
	ds_read_b128 v[184:187], v151 offset:17408
	ds_read_b128 v[188:191], v151 offset:18432
	ds_read_b128 v[192:195], v151 offset:19456
	ds_read_b128 v[196:199], v151 offset:20480
	ds_read_b128 v[200:203], v151 offset:21504
	ds_read_b128 v[204:207], v151 offset:22528
	ds_read_b128 v[208:211], v151 offset:23552
	global_load_lds_dwordx4 v[144:145], off
	s_add_i32 m0, s50, 0x2000
	s_add_u32 s50, s28, 0x80000
	v_lshl_add_u64 v[212:213], s[28:29], 0, v[130:131]
	s_addc_u32 s51, s29, 0
	s_add_i32 s52, s44, s30
	global_load_lds_dwordx4 v[212:213], off
	v_lshl_add_u64 v[214:215], s[50:51], 0, v[128:129]
	s_mov_b32 m0, s52
	v_lshl_add_u64 v[216:217], s[34:35], 0, v[130:131]
	global_load_lds_dwordx4 v[214:215], off
	v_lshl_add_u64 v[214:215], s[50:51], 0, v[130:131]
	s_add_i32 m0, s52, 0x2000
	s_nop 0
	global_load_lds_dwordx4 v[214:215], off
	v_lshl_add_u64 v[214:215], s[34:35], 0, v[128:129]
	s_mov_b32 m0, s25
	s_nop 0
	global_load_lds_dwordx4 v[214:215], off
	s_mov_b32 m0, s36
	s_nop 0
	global_load_lds_dwordx4 v[216:217], off
	s_waitcnt vmcnt(8)
	s_waitcnt lgkmcnt(0)
	s_barrier
	s_setprio 1
	s_waitcnt lgkmcnt(0)
	v_mfma_f32_16x16x32_bf16 v[60:63], v[140:143], v[180:183], v[60:63]
	v_mfma_f32_16x16x32_bf16 v[60:63], v[152:155], v[184:187], v[60:63]
	v_mfma_f32_16x16x32_bf16 v[52:55], v[152:155], v[192:195], v[52:55]
	v_mfma_f32_16x16x32_bf16 v[52:55], v[140:143], v[188:191], v[52:55]
	v_mfma_f32_16x16x32_bf16 v[44:47], v[140:143], v[196:199], v[44:47]
	v_mfma_f32_16x16x32_bf16 v[44:47], v[152:155], v[200:203], v[44:47]
	v_mfma_f32_16x16x32_bf16 v[28:31], v[152:155], v[208:211], v[28:31]
	v_mfma_f32_16x16x32_bf16 v[28:31], v[140:143], v[204:207], v[28:31]
	v_mfma_f32_16x16x32_bf16 v[16:19], v[156:159], v[204:207], v[16:19]
	v_mfma_f32_16x16x32_bf16 v[16:19], v[160:163], v[208:211], v[16:19]
	v_mfma_f32_16x16x32_bf16 v[36:39], v[160:163], v[200:203], v[36:39]
	v_mfma_f32_16x16x32_bf16 v[36:39], v[156:159], v[196:199], v[36:39]
	v_mfma_f32_16x16x32_bf16 v[48:51], v[156:159], v[188:191], v[48:51]
	v_mfma_f32_16x16x32_bf16 v[48:51], v[160:163], v[192:195], v[48:51]
	v_mfma_f32_16x16x32_bf16 v[56:59], v[160:163], v[184:187], v[56:59]
	v_mfma_f32_16x16x32_bf16 v[56:59], v[156:159], v[180:183], v[56:59]
	s_setprio 0
	s_setprio 1
	v_mfma_f32_16x16x32_bf16 v[40:43], v[164:167], v[180:183], v[40:43]
	v_mfma_f32_16x16x32_bf16 v[40:43], v[168:171], v[184:187], v[40:43]
	v_mfma_f32_16x16x32_bf16 v[24:27], v[168:171], v[192:195], v[24:27]
	v_mfma_f32_16x16x32_bf16 v[24:27], v[164:167], v[188:191], v[24:27]
	v_mfma_f32_16x16x32_bf16 v[12:15], v[164:167], v[196:199], v[12:15]
	v_mfma_f32_16x16x32_bf16 v[12:15], v[168:171], v[200:203], v[12:15]
	v_mfma_f32_16x16x32_bf16 v[4:7], v[168:171], v[208:211], v[4:7]
	v_mfma_f32_16x16x32_bf16 v[4:7], v[164:167], v[204:207], v[4:7]
	v_mfma_f32_16x16x32_bf16 v[0:3], v[172:175], v[204:207], v[0:3]
	v_mfma_f32_16x16x32_bf16 v[0:3], v[176:179], v[208:211], v[0:3]
	v_mfma_f32_16x16x32_bf16 v[8:11], v[176:179], v[200:203], v[8:11]
	v_mfma_f32_16x16x32_bf16 v[8:11], v[172:175], v[196:199], v[8:11]
	v_mfma_f32_16x16x32_bf16 v[20:23], v[172:175], v[188:191], v[20:23]
	v_mfma_f32_16x16x32_bf16 v[20:23], v[176:179], v[192:195], v[20:23]
	v_mfma_f32_16x16x32_bf16 v[32:35], v[176:179], v[184:187], v[32:35]
	v_mfma_f32_16x16x32_bf16 v[32:35], v[172:175], v[180:183], v[32:35]
	s_setprio 0
	s_barrier
; #define PG8_STAGE(bufoff, gbase, voff) do { _Pragma("unroll") for (int _i = 0; _i < 2; ++_i) \
;         __builtin_amdgcn_global_load_lds((const unsigned*)((const char*)(gbase) + (voff)[_i]), (PG8_LAS unsigned*)(lds + (bufoff) + ldsw + _i * 8192), 16, 0, 0); } while (0)
; #define PG8_LDA(dst, b, h) do { _Pragma("unroll") for (int m = 0; m < 4; ++m) _Pragma("unroll") for (int k = 0; k < 2; ++k) dst[m][k] = *(const PG8_LAS bf16x8*)(lds + PG8_SA(b, h) + aoff + m * 2048 + k * 1024); } while (0)
; #define PG8_LDB(dst, b, h) do { _Pragma("unroll") for (int n = 0; n < 2; ++n) _Pragma("unroll") for (int k = 0; k < 2; ++k) dst[n][k] = *(const PG8_LAS bf16x8*)(lds + PG8_SB(b, h) + boff + n * 2048 + k * 1024); } while (0)
; #define PG8_MMA(ai, bj, At, Bt) do { __builtin_amdgcn_s_setprio(1); _Pragma("unroll") for (int m = 0; m < 4; ++m) _Pragma("unroll") for (int n = 0; n < 2; ++n) _Pragma("unroll") for (int k = 0; k < 2; ++k) \
;         acc[ai][bj][m][n] = __builtin_amdgcn_mfma_f32_16x16x32_bf16(Bt[n][k], At[m][k], acc[ai][bj][m][n], 0, 0, 0); __builtin_amdgcn_s_setprio(0); } while (0)
; #define PG8_WAIT_V(n) asm volatile("s_waitcnt vmcnt(" #n ")" ::: "memory")
; #define PG8_WAIT_L(n) asm volatile("s_waitcnt lgkmcnt(" #n ")" ::: "memory")
; #define PG8_BAR __builtin_amdgcn_s_barrier()
; #define PG8_SCHED __builtin_amdgcn_sched_barrier(0)
; template <class Epi, class Sched, bool ALIGN_EPI = false, bool SP2 = false>
; __device__ __forceinline__ void gemm_phase(PG8_LAS unsigned char* lds, const Gemm g, const Sched& S, const Epi& E) {
;     ...
;             PG8_LDB(B0, 1, 0); PG8_LDB(B1, 1, 1); PG8_SCHED; PG8_LDA(At, 1, 0); PG8_STAGE(PG8_SA(0, 1), a2 + hstep, voffA);
;             PG8_WAIT_V(8); PG8_WAIT_L(0); PG8_BAR; PG8_MMA(0, 0, At, B0); PG8_MMA(0, 1, At, B1); PG8_BAR; PG8_SCHED;
;             PG8_LDA(At, 1, 1); PG8_STAGE(PG8_SB(1, 0), b3, voffB); PG8_STAGE(PG8_SB(1, 1), b3 + hstep, voffB); PG8_STAGE(PG8_SA(1, 0), a3, voffA);
;             PG8_WAIT_V(8); PG8_WAIT_L(0); PG8_BAR; PG8_MMA(1, 0, At, B0); PG8_MMA(1, 1, At, B1); PG8_BAR; PG8_SCHED;
	s_add_i32 s50, 0, 0x18000
	s_add_i32 s51, 0, 0x1c000
	v_add_u32_e32 v160, s50, v147
	v_add_u32_e32 v176, s51, v147
	ds_read_b128 v[140:143], v160
	ds_read_b128 v[152:155], v160 offset:1024
	ds_read_b128 v[156:159], v160 offset:2048
	ds_read_b128 v[160:163], v160 offset:3072
	ds_read_b128 v[164:167], v176
	ds_read_b128 v[168:171], v176 offset:1024
	ds_read_b128 v[172:175], v176 offset:2048
	ds_read_b128 v[176:179], v176 offset:3072
	s_add_u32 s34, s34, 0x80000
	s_addc_u32 s35, s35, 0
	s_mov_b32 m0, s37
	v_lshl_add_u64 v[218:219], s[34:35], 0, v[128:129]
	ds_read_b128 v[180:183], v151 offset:32768
	ds_read_b128 v[184:187], v151 offset:33792
	ds_read_b128 v[188:191], v151 offset:34816
	ds_read_b128 v[192:195], v151 offset:35840
	ds_read_b128 v[196:199], v151 offset:36864
	ds_read_b128 v[200:203], v151 offset:37888
	ds_read_b128 v[204:207], v151 offset:38912
	ds_read_b128 v[208:211], v151 offset:39936
	global_load_lds_dwordx4 v[218:219], off
	v_lshl_add_u64 v[218:219], s[34:35], 0, v[130:131]
	s_mov_b32 m0, s38
	s_nop 0
	global_load_lds_dwordx4 v[218:219], off
	s_waitcnt vmcnt(8)
	s_waitcnt lgkmcnt(0)
	s_barrier
	s_setprio 1
	s_waitcnt lgkmcnt(0)
	v_mfma_f32_16x16x32_bf16 v[124:127], v[140:143], v[180:183], v[124:127]
	v_mfma_f32_16x16x32_bf16 v[124:127], v[152:155], v[184:187], v[124:127]
	v_mfma_f32_16x16x32_bf16 v[116:119], v[152:155], v[192:195], v[116:119]
	v_mfma_f32_16x16x32_bf16 v[116:119], v[140:143], v[188:191], v[116:119]
	v_mfma_f32_16x16x32_bf16 v[108:111], v[140:143], v[196:199], v[108:111]
	v_mfma_f32_16x16x32_bf16 v[108:111], v[152:155], v[200:203], v[108:111]
	v_mfma_f32_16x16x32_bf16 v[92:95], v[152:155], v[208:211], v[92:95]
	v_mfma_f32_16x16x32_bf16 v[92:95], v[140:143], v[204:207], v[92:95]
	v_mfma_f32_16x16x32_bf16 v[80:83], v[156:159], v[204:207], v[80:83]
	v_mfma_f32_16x16x32_bf16 v[80:83], v[160:163], v[208:211], v[80:83]
	v_mfma_f32_16x16x32_bf16 v[100:103], v[160:163], v[200:203], v[100:103]
	v_mfma_f32_16x16x32_bf16 v[100:103], v[156:159], v[196:199], v[100:103]
	v_mfma_f32_16x16x32_bf16 v[112:115], v[156:159], v[188:191], v[112:115]
	v_mfma_f32_16x16x32_bf16 v[112:115], v[160:163], v[192:195], v[112:115]
	v_mfma_f32_16x16x32_bf16 v[120:123], v[160:163], v[184:187], v[120:123]
	v_mfma_f32_16x16x32_bf16 v[120:123], v[156:159], v[180:183], v[120:123]
	s_setprio 0
	s_setprio 1
	v_mfma_f32_16x16x32_bf16 v[104:107], v[164:167], v[180:183], v[104:107]
	v_mfma_f32_16x16x32_bf16 v[104:107], v[168:171], v[184:187], v[104:107]
	v_mfma_f32_16x16x32_bf16 v[88:91], v[168:171], v[192:195], v[88:91]
	v_mfma_f32_16x16x32_bf16 v[88:91], v[164:167], v[188:191], v[88:91]
	v_mfma_f32_16x16x32_bf16 v[76:79], v[164:167], v[196:199], v[76:79]
	v_mfma_f32_16x16x32_bf16 v[76:79], v[168:171], v[200:203], v[76:79]
	v_mfma_f32_16x16x32_bf16 v[68:71], v[168:171], v[208:211], v[68:71]
	v_mfma_f32_16x16x32_bf16 v[68:71], v[164:167], v[204:207], v[68:71]
	v_mfma_f32_16x16x32_bf16 v[64:67], v[172:175], v[204:207], v[64:67]
	v_mfma_f32_16x16x32_bf16 v[64:67], v[176:179], v[208:211], v[64:67]
	v_mfma_f32_16x16x32_bf16 v[72:75], v[176:179], v[200:203], v[72:75]
	v_mfma_f32_16x16x32_bf16 v[72:75], v[172:175], v[196:199], v[72:75]
	v_mfma_f32_16x16x32_bf16 v[84:87], v[172:175], v[188:191], v[84:87]
	v_mfma_f32_16x16x32_bf16 v[84:87], v[176:179], v[192:195], v[84:87]
	v_mfma_f32_16x16x32_bf16 v[96:99], v[176:179], v[184:187], v[96:99]
	v_mfma_f32_16x16x32_bf16 v[96:99], v[172:175], v[180:183], v[96:99]
	s_setprio 0
	s_barrier
	s_add_i32 s34, s50, s30
	v_lshl_add_u64 v[144:145], v[144:145], 0, s[4:5]
	s_mov_b32 m0, s34
	ds_read_b128 v[180:183], v151 offset:49152
	ds_read_b128 v[184:187], v151 offset:50176
	ds_read_b128 v[188:191], v151 offset:51200
	ds_read_b128 v[192:195], v151 offset:52224
	ds_read_b128 v[196:199], v151 offset:53248
	ds_read_b128 v[200:203], v151 offset:54272
	ds_read_b128 v[204:207], v151 offset:55296
	ds_read_b128 v[208:211], v151 offset:56320
	global_load_lds_dwordx4 v[144:145], off
	s_add_i32 m0, s34, 0x2000
	s_add_u32 s28, s28, 0x80080
	v_lshl_add_u64 v[144:145], v[212:213], 0, s[4:5]
	s_addc_u32 s29, s29, 0
	s_add_i32 s34, s51, s30
	global_load_lds_dwordx4 v[144:145], off
	v_lshl_add_u64 v[144:145], s[28:29], 0, v[128:129]
	s_mov_b32 m0, s34
	s_nop 0
	global_load_lds_dwordx4 v[144:145], off
	v_lshl_add_u64 v[144:145], s[28:29], 0, v[130:131]
	s_add_i32 m0, s34, 0x2000
	s_nop 0
	global_load_lds_dwordx4 v[144:145], off
	v_lshl_add_u64 v[144:145], v[214:215], 0, s[4:5]
	s_mov_b32 m0, s41
	s_nop 0
	global_load_lds_dwordx4 v[144:145], off
	v_lshl_add_u64 v[144:145], v[216:217], 0, s[4:5]
	s_mov_b32 m0, s42
	s_nop 0
	global_load_lds_dwordx4 v[144:145], off
	s_waitcnt vmcnt(8)
	s_waitcnt lgkmcnt(0)
	s_barrier
; #define PG8_STAGE(bufoff, gbase, voff) do { _Pragma("unroll") for (int _i = 0; _i < 2; ++_i) \
;         __builtin_amdgcn_global_load_lds((const unsigned*)((const char*)(gbase) + (voff)[_i]), (PG8_LAS unsigned*)(lds + (bufoff) + ldsw + _i * 8192), 16, 0, 0); } while (0)
; #define PG8_LDA(dst, b, h) do { _Pragma("unroll") for (int m = 0; m < 4; ++m) _Pragma("unroll") for (int k = 0; k < 2; ++k) dst[m][k] = *(const PG8_LAS bf16x8*)(lds + PG8_SA(b, h) + aoff + m * 2048 + k * 1024); } while (0)
; #define PG8_WAIT_V(n) asm volatile("s_waitcnt vmcnt(" #n ")" ::: "memory")
; #define PG8_BAR __builtin_amdgcn_s_barrier()
;     __device__ __forceinline__ void operator()(const f32x4 (&acc)[2][2][4][2], const Unit& u, int wr, int wc, int fr, int fq) const {
;         const int row0 = u.pm * BM + wr * 64 + fr, col0 = u.pn * BM + wc * 32 + 4 * fq;
; #pragma unroll
;         for (int ai = 0; ai < 2; ++ai) {
;             f32x4 res[4][2][2];
; #pragma unroll
;             for (int m = 0; m < 4; ++m) { const size_t off = (size_t)(row0 + ai * HALF + m * 16) * ldc + col0;
; #pragma unroll
;                 for (int bj = 0; bj < 2; ++bj)
; #pragma unroll
;                     for (int n = 0; n < 2; ++n) res[m][bj][n] = *(const f32x4*)(base + off + bj * HALF + n * 16); }
; template <class Epi, class Sched, bool ALIGN_EPI = false, bool SP2 = false>
; __device__ __forceinline__ void gemm_phase(PG8_LAS unsigned char* lds, const Gemm g, const Sched& S, const Epi& E) {
;     ...
;             PG8_WAIT_V(8); PG8_WAIT_L(0); PG8_BAR; PG8_MMA(0, 0, At, B0); PG8_MMA(0, 1, At, B1); PG8_BAR; PG8_SCHED;
;             PG8_LDA(At, 0, 1); PG8_STAGE(PG8_SB(0, 0), b2, voffB); PG8_STAGE(PG8_SB(0, 1), b2 + hstep, voffB); PG8_STAGE(PG8_SA(0, 0), a2, voffA);
;             PG8_WAIT_V(8); PG8_WAIT_L(0); PG8_BAR; PG8_MMA(1, 0, At, B0); PG8_MMA(1, 1, At, B1); PG8_BAR; PG8_SCHED;
;             PG8_LDB(B0, 1, 0); PG8_LDB(B1, 1, 1); PG8_SCHED; PG8_LDA(At, 1, 0); PG8_STAGE(PG8_SA(0, 1), a2 + hstep, voffA);
;             PG8_WAIT_V(8); PG8_WAIT_L(0); PG8_BAR; PG8_MMA(0, 0, At, B0); PG8_MMA(0, 1, At, B1); PG8_BAR; PG8_SCHED;
;             PG8_LDA(At, 1, 1); PG8_STAGE(PG8_SB(1, 0), b3, voffB); PG8_STAGE(PG8_SB(1, 1), b3 + hstep, voffB); PG8_STAGE(PG8_SA(1, 0), a3, voffA);
;             PG8_WAIT_V(8); PG8_WAIT_L(0); PG8_BAR; PG8_MMA(1, 0, At, B0); PG8_MMA(1, 1, At, B1); PG8_BAR; PG8_SCHED;
	s_setprio 1
	s_waitcnt lgkmcnt(0)
	v_mfma_f32_16x16x32_bf16 v[60:63], v[140:143], v[180:183], v[60:63]
	v_mfma_f32_16x16x32_bf16 v[60:63], v[152:155], v[184:187], v[60:63]
	v_mfma_f32_16x16x32_bf16 v[52:55], v[152:155], v[192:195], v[52:55]
	v_mfma_f32_16x16x32_bf16 v[52:55], v[140:143], v[188:191], v[52:55]
	v_mfma_f32_16x16x32_bf16 v[44:47], v[140:143], v[196:199], v[44:47]
	v_mfma_f32_16x16x32_bf16 v[44:47], v[152:155], v[200:203], v[44:47]
	v_mfma_f32_16x16x32_bf16 v[28:31], v[152:155], v[208:211], v[28:31]
	v_mfma_f32_16x16x32_bf16 v[28:31], v[140:143], v[204:207], v[28:31]
	v_mfma_f32_16x16x32_bf16 v[16:19], v[156:159], v[204:207], v[16:19]
	v_mfma_f32_16x16x32_bf16 v[16:19], v[160:163], v[208:211], v[16:19]
	v_mfma_f32_16x16x32_bf16 v[36:39], v[160:163], v[200:203], v[36:39]
	v_mfma_f32_16x16x32_bf16 v[36:39], v[156:159], v[196:199], v[36:39]
	v_mfma_f32_16x16x32_bf16 v[48:51], v[156:159], v[188:191], v[48:51]
	v_mfma_f32_16x16x32_bf16 v[48:51], v[160:163], v[192:195], v[48:51]
	v_mfma_f32_16x16x32_bf16 v[56:59], v[160:163], v[184:187], v[56:59]
	v_mfma_f32_16x16x32_bf16 v[56:59], v[156:159], v[180:183], v[56:59]
	s_setprio 0
	s_setprio 1
	v_mfma_f32_16x16x32_bf16 v[40:43], v[164:167], v[180:183], v[40:43]
	v_mfma_f32_16x16x32_bf16 v[40:43], v[168:171], v[184:187], v[40:43]
	v_mfma_f32_16x16x32_bf16 v[24:27], v[168:171], v[192:195], v[24:27]
	v_mfma_f32_16x16x32_bf16 v[24:27], v[164:167], v[188:191], v[24:27]
	v_mfma_f32_16x16x32_bf16 v[12:15], v[164:167], v[196:199], v[12:15]
	v_mfma_f32_16x16x32_bf16 v[12:15], v[168:171], v[200:203], v[12:15]
	v_mfma_f32_16x16x32_bf16 v[4:7], v[168:171], v[208:211], v[4:7]
	v_mfma_f32_16x16x32_bf16 v[4:7], v[164:167], v[204:207], v[4:7]
	v_mfma_f32_16x16x32_bf16 v[0:3], v[172:175], v[204:207], v[0:3]
	v_mfma_f32_16x16x32_bf16 v[0:3], v[176:179], v[208:211], v[0:3]
	v_mfma_f32_16x16x32_bf16 v[8:11], v[176:179], v[200:203], v[8:11]
	v_mfma_f32_16x16x32_bf16 v[8:11], v[172:175], v[196:199], v[8:11]
	v_mfma_f32_16x16x32_bf16 v[20:23], v[172:175], v[188:191], v[20:23]
	v_mfma_f32_16x16x32_bf16 v[20:23], v[176:179], v[192:195], v[20:23]
	v_mfma_f32_16x16x32_bf16 v[32:35], v[176:179], v[184:187], v[32:35]
	v_mfma_f32_16x16x32_bf16 v[32:35], v[172:175], v[180:183], v[32:35]
	s_setprio 0
	s_barrier
	s_add_i32 s49, s49, 2
	s_add_u32 s26, s26, 0x100
	s_addc_u32 s27, s27, 0
	s_add_u32 s47, s47, 0x100
	s_addc_u32 s48, s48, 0
	s_cmp_gt_u32 s49, 29
	s_cbranch_scc0 .LBB0_458
.Lp3_k2_exit:
	s_and_b64 vcc, exec, s[6:7]
	s_cbranch_vccz .LBB0_461
	s_barrier
.LBB0_461:
	s_cmp_eq_u32 s101, 1
	s_cbranch_scc1 .Lp3_epi_first
	s_cmp_eq_u32 s101, 2
	s_cbranch_scc1 .Lp3_epi_stream
	v_lshl_add_u32 v200, s24, 8, v146
	v_lshl_or_b32 v140, s45, 8, v148
	v_ashrrev_i32_e32 v201, 31, v200
	v_ashrrev_i32_e32 v141, 31, v140
	v_readlane_b32 s48, v254, 0
	v_lshlrev_b64 v[144:145], 13, v[200:201]
	v_or_b32_e32 v168, 16, v200
	v_or_b32_e32 v184, 32, v200
	v_or_b32_e32 v200, 48, v200
	v_lshlrev_b64 v[140:141], 2, v[140:141]
	v_readlane_b32 s49, v254, 1
	v_ashrrev_i32_e32 v169, 31, v168
	v_ashrrev_i32_e32 v185, 31, v184
	v_ashrrev_i32_e32 v201, 31, v200
	v_lshl_add_u64 v[142:143], s[48:49], 0, v[140:141]
	v_lshlrev_b64 v[216:217], 13, v[168:169]
	v_lshlrev_b64 v[218:219], 13, v[184:185]
	v_lshlrev_b64 v[220:221], 13, v[200:201]
	v_lshl_add_u64 v[164:165], v[142:143], 0, v[144:145]
	v_lshl_add_u64 v[180:181], v[142:143], 0, v[216:217]
	v_lshl_add_u64 v[196:197], v[142:143], 0, v[218:219]
	v_lshl_add_u64 v[212:213], v[142:143], 0, v[220:221]
	global_load_dwordx4 v[152:155], v[164:165], off
	global_load_dwordx4 v[156:159], v[164:165], off offset:64
	global_load_dwordx4 v[160:163], v[164:165], off offset:512
	s_nop 0
	global_load_dwordx4 v[164:167], v[164:165], off offset:576
	s_nop 0
	global_load_dwordx4 v[168:171], v[180:181], off
	global_load_dwordx4 v[172:175], v[180:181], off offset:64
	global_load_dwordx4 v[176:179], v[180:181], off offset:512
	s_nop 0
	global_load_dwordx4 v[180:183], v[180:181], off offset:576
	s_nop 0
	global_load_dwordx4 v[184:187], v[196:197], off
	global_load_dwordx4 v[188:191], v[196:197], off offset:64
	global_load_dwordx4 v[192:195], v[196:197], off offset:512
	s_nop 0
	global_load_dwordx4 v[196:199], v[196:197], off offset:576
	s_nop 0
	global_load_dwordx4 v[200:203], v[212:213], off
	global_load_dwordx4 v[204:207], v[212:213], off offset:64
	global_load_dwordx4 v[208:211], v[212:213], off offset:512
	s_nop 0
	global_load_dwordx4 v[212:215], v[212:213], off offset:576
	v_lshl_add_u64 v[222:223], s[70:71], 0, v[144:145]
	v_lshl_add_u64 v[220:221], s[70:71], 0, v[220:221]
	v_lshl_add_u64 v[222:223], v[222:223], 0, v[140:141]
	v_lshl_add_u64 v[216:217], s[70:71], 0, v[216:217]
	v_lshl_add_u64 v[218:219], s[70:71], 0, v[218:219]
	v_lshl_add_u64 v[220:221], v[220:221], 0, v[140:141]
	v_lshl_add_u64 v[216:217], v[216:217], 0, v[140:141]
	v_lshl_add_u64 v[218:219], v[218:219], 0, v[140:141]
	s_andn2_b64 vcc, exec, s[0:1]
	s_mov_b64 s[0:1], -1
	v_readlane_b32 s50, v254, 2
	v_readlane_b32 s51, v254, 3
	v_readlane_b32 s52, v254, 4
	v_readlane_b32 s53, v254, 5
	v_readlane_b32 s54, v254, 6
	v_readlane_b32 s55, v254, 7
	v_readlane_b32 s56, v254, 8
	v_readlane_b32 s57, v254, 9
	v_readlane_b32 s58, v254, 10
	v_readlane_b32 s59, v254, 11
	v_readlane_b32 s60, v254, 12
	v_readlane_b32 s61, v254, 13
	v_readlane_b32 s62, v254, 14
	v_readlane_b32 s63, v254, 15
	s_waitcnt vmcnt(0)
;     __device__ __forceinline__ void operator()(const f32x4 (&acc)[2][2][4][2], const Unit& u, int wr, int wc, int fr, int fq) const {
;         const int row0 = u.pm * BM + wr * 64 + fr, col0 = u.pn * BM + wc * 32 + 4 * fq;
; #pragma unroll
;         for (int ai = 0; ai < 2; ++ai) {
;             f32x4 res[4][2][2];
; #pragma unroll
;             for (int m = 0; m < 4; ++m) { const size_t off = (size_t)(row0 + ai * HALF + m * 16) * ldc + col0;
; #pragma unroll
;                 for (int bj = 0; bj < 2; ++bj)
; #pragma unroll
;                     for (int n = 0; n < 2; ++n) res[m][bj][n] = *(const f32x4*)(base + off + bj * HALF + n * 16); }
;             asm volatile("" ::: "memory");
; #pragma unroll
;             for (int m = 0; m < 4; ++m) { const size_t off = (size_t)(row0 + ai * HALF + m * 16) * ldc + col0;
; #pragma unroll
;                 for (int bj = 0; bj < 2; ++bj)
; #pragma unroll
;                     for (int n = 0; n < 2; ++n) *(f32x4*)(out + off + bj * HALF + n * 16) = res[m][bj][n] + acc[ai][bj][m][n]; }
;             asm volatile("" ::: "memory");
;         }
	v_pk_add_f32 v[126:127], v[126:127], v[154:155]
	v_pk_add_f32 v[124:125], v[124:125], v[152:153]
	v_pk_add_f32 v[122:123], v[122:123], v[158:159]
	v_pk_add_f32 v[120:121], v[120:121], v[156:157]
	v_pk_add_f32 v[106:107], v[106:107], v[162:163]
	v_pk_add_f32 v[70:71], v[70:71], v[210:211]
	v_pk_add_f32 v[68:69], v[68:69], v[208:209]
	v_pk_add_f32 v[66:67], v[66:67], v[214:215]
	v_pk_add_f32 v[64:65], v[64:65], v[212:213]
	v_pk_add_f32 v[104:105], v[104:105], v[160:161]
	v_pk_add_f32 v[98:99], v[98:99], v[166:167]
	v_pk_add_f32 v[96:97], v[96:97], v[164:165]
	v_pk_add_f32 v[118:119], v[118:119], v[170:171]
	v_pk_add_f32 v[116:117], v[116:117], v[168:169]
	v_pk_add_f32 v[114:115], v[114:115], v[174:175]
	v_pk_add_f32 v[112:113], v[112:113], v[172:173]
	v_pk_add_f32 v[90:91], v[90:91], v[178:179]
	v_pk_add_f32 v[88:89], v[88:89], v[176:177]
	v_pk_add_f32 v[86:87], v[86:87], v[182:183]
	v_pk_add_f32 v[84:85], v[84:85], v[180:181]
	v_pk_add_f32 v[110:111], v[110:111], v[186:187]
	v_pk_add_f32 v[108:109], v[108:109], v[184:185]
	v_pk_add_f32 v[102:103], v[102:103], v[190:191]
	v_pk_add_f32 v[100:101], v[100:101], v[188:189]
	v_pk_add_f32 v[78:79], v[78:79], v[194:195]
	v_pk_add_f32 v[76:77], v[76:77], v[192:193]
	v_pk_add_f32 v[74:75], v[74:75], v[198:199]
	v_pk_add_f32 v[72:73], v[72:73], v[196:197]
	v_pk_add_f32 v[94:95], v[94:95], v[202:203]
	v_pk_add_f32 v[92:93], v[92:93], v[200:201]
	v_pk_add_f32 v[82:83], v[82:83], v[206:207]
	v_pk_add_f32 v[80:81], v[80:81], v[204:205]
	global_store_dwordx4 v[222:223], v[124:127], off
	global_store_dwordx4 v[222:223], v[120:123], off offset:64
	global_store_dwordx4 v[222:223], v[104:107], off offset:512
	global_store_dwordx4 v[222:223], v[96:99], off offset:576
	global_store_dwordx4 v[216:217], v[116:119], off
	global_store_dwordx4 v[216:217], v[112:115], off offset:64
	global_store_dwordx4 v[216:217], v[88:91], off offset:512
	global_store_dwordx4 v[216:217], v[84:87], off offset:576
	global_store_dwordx4 v[218:219], v[108:111], off
	global_store_dwordx4 v[218:219], v[100:103], off offset:64
	global_store_dwordx4 v[218:219], v[76:79], off offset:512
	global_store_dwordx4 v[218:219], v[72:75], off offset:576
	global_store_dwordx4 v[220:221], v[92:95], off
	global_store_dwordx4 v[220:221], v[80:83], off offset:64
	global_store_dwordx4 v[220:221], v[68:71], off offset:512
	global_store_dwordx4 v[220:221], v[64:67], off offset:576
	v_lshl_add_u64 v[152:153], v[144:145], 0, s[8:9]
	v_lshl_add_u64 v[154:155], v[144:145], 0, s[10:11]
	v_lshl_add_u64 v[156:157], v[144:145], 0, s[12:13]
	v_lshl_add_u64 v[144:145], v[144:145], 0, s[14:15]
	v_lshl_add_u64 v[80:81], v[142:143], 0, v[152:153]
	v_lshl_add_u64 v[96:97], v[142:143], 0, v[154:155]
	v_lshl_add_u64 v[108:109], v[142:143], 0, v[156:157]
	v_lshl_add_u64 v[124:125], v[142:143], 0, v[144:145]
	global_load_dwordx4 v[64:67], v[80:81], off
	global_load_dwordx4 v[68:71], v[80:81], off offset:64
	global_load_dwordx4 v[72:75], v[80:81], off offset:512
	global_load_dwordx4 v[76:79], v[80:81], off offset:576
	s_nop 0
	global_load_dwordx4 v[80:83], v[96:97], off
	global_load_dwordx4 v[84:87], v[96:97], off offset:64
	global_load_dwordx4 v[88:91], v[96:97], off offset:512
	global_load_dwordx4 v[92:95], v[96:97], off offset:576
	s_nop 0
	global_load_dwordx4 v[96:99], v[108:109], off
	global_load_dwordx4 v[100:103], v[108:109], off offset:64
	global_load_dwordx4 v[104:107], v[108:109], off offset:512
	s_nop 0
	global_load_dwordx4 v[108:111], v[108:109], off offset:576
	s_nop 0
	global_load_dwordx4 v[112:115], v[124:125], off
	global_load_dwordx4 v[116:119], v[124:125], off offset:64
	global_load_dwordx4 v[120:123], v[124:125], off offset:512
	s_nop 0
	global_load_dwordx4 v[124:127], v[124:125], off offset:576
	v_lshl_add_u64 v[142:143], s[70:71], 0, v[152:153]
	v_lshl_add_u64 v[152:153], s[70:71], 0, v[154:155]
	v_lshl_add_u64 v[154:155], s[70:71], 0, v[156:157]
	v_lshl_add_u64 v[144:145], s[70:71], 0, v[144:145]
	v_lshl_add_u64 v[142:143], v[142:143], 0, v[140:141]
	v_lshl_add_u64 v[152:153], v[152:153], 0, v[140:141]
	v_lshl_add_u64 v[154:155], v[154:155], 0, v[140:141]
	v_lshl_add_u64 v[140:141], v[144:145], 0, v[140:141]
	s_waitcnt vmcnt(15)
	v_pk_add_f32 v[62:63], v[62:63], v[66:67]
	v_pk_add_f32 v[60:61], v[60:61], v[64:65]
	s_waitcnt vmcnt(14)
	v_pk_add_f32 v[58:59], v[58:59], v[70:71]
	v_pk_add_f32 v[56:57], v[56:57], v[68:69]
	s_waitcnt vmcnt(13)
	v_pk_add_f32 v[42:43], v[42:43], v[74:75]
	s_waitcnt vmcnt(1)
	v_pk_add_f32 v[6:7], v[6:7], v[122:123]
	v_pk_add_f32 v[4:5], v[4:5], v[120:121]
	s_waitcnt vmcnt(0)
	v_pk_add_f32 v[2:3], v[2:3], v[126:127]
	v_pk_add_f32 v[0:1], v[0:1], v[124:125]
	v_pk_add_f32 v[40:41], v[40:41], v[72:73]
	v_pk_add_f32 v[34:35], v[34:35], v[78:79]
	v_pk_add_f32 v[32:33], v[32:33], v[76:77]
	v_pk_add_f32 v[54:55], v[54:55], v[82:83]
	v_pk_add_f32 v[52:53], v[52:53], v[80:81]
	v_pk_add_f32 v[50:51], v[50:51], v[86:87]
	v_pk_add_f32 v[48:49], v[48:49], v[84:85]
	v_pk_add_f32 v[26:27], v[26:27], v[90:91]
	v_pk_add_f32 v[24:25], v[24:25], v[88:89]
	v_pk_add_f32 v[22:23], v[22:23], v[94:95]
	v_pk_add_f32 v[20:21], v[20:21], v[92:93]
	v_pk_add_f32 v[46:47], v[46:47], v[98:99]
	v_pk_add_f32 v[44:45], v[44:45], v[96:97]
	v_pk_add_f32 v[38:39], v[38:39], v[102:103]
	v_pk_add_f32 v[36:37], v[36:37], v[100:101]
	v_pk_add_f32 v[14:15], v[14:15], v[106:107]
	v_pk_add_f32 v[12:13], v[12:13], v[104:105]
	v_pk_add_f32 v[10:11], v[10:11], v[110:111]
	v_pk_add_f32 v[8:9], v[8:9], v[108:109]
	v_pk_add_f32 v[30:31], v[30:31], v[114:115]
	v_pk_add_f32 v[28:29], v[28:29], v[112:113]
	v_pk_add_f32 v[18:19], v[18:19], v[118:119]
	v_pk_add_f32 v[16:17], v[16:17], v[116:117]
	global_store_dwordx4 v[142:143], v[60:63], off
	global_store_dwordx4 v[142:143], v[56:59], off offset:64
	global_store_dwordx4 v[142:143], v[40:43], off offset:512
	global_store_dwordx4 v[142:143], v[32:35], off offset:576
	global_store_dwordx4 v[152:153], v[52:55], off
	global_store_dwordx4 v[152:153], v[48:51], off offset:64
	global_store_dwordx4 v[152:153], v[24:27], off offset:512
	global_store_dwordx4 v[152:153], v[20:23], off offset:576
	global_store_dwordx4 v[154:155], v[44:47], off
	global_store_dwordx4 v[154:155], v[36:39], off offset:64
	global_store_dwordx4 v[154:155], v[12:15], off offset:512
	global_store_dwordx4 v[154:155], v[8:11], off offset:576
	global_store_dwordx4 v[140:141], v[28:31], off
	global_store_dwordx4 v[140:141], v[16:19], off offset:64
	global_store_dwordx4 v[140:141], v[4:7], off offset:512
	global_store_dwordx4 v[140:141], v[0:3], off offset:576

; #define PG8_STAGE(bufoff, gbase, voff) do { _Pragma("unroll") for (int _i = 0; _i < 2; ++_i) \
;         __builtin_amdgcn_global_load_lds((const unsigned*)((const char*)(gbase) + (voff)[_i]), (PG8_LAS unsigned*)(lds + (bufoff) + ldsw + _i * 8192), 16, 0, 0); } while (0)
; #define PG8_LDA(dst, b, h) do { _Pragma("unroll") for (int m = 0; m < 4; ++m) _Pragma("unroll") for (int k = 0; k < 2; ++k) dst[m][k] = *(const PG8_LAS bf16x8*)(lds + PG8_SA(b, h) + aoff + m * 2048 + k * 1024); } while (0)
; #define PG8_LDB(dst, b, h) do { _Pragma("unroll") for (int n = 0; n < 2; ++n) _Pragma("unroll") for (int k = 0; k < 2; ++k) dst[n][k] = *(const PG8_LAS bf16x8*)(lds + PG8_SB(b, h) + boff + n * 2048 + k * 1024); } while (0)
; #define PG8_SCHED __builtin_amdgcn_sched_barrier(0)
;     __device__ __forceinline__ void operator()(const f32x4 (&acc)[2][2][4][2], const Unit& u, int wr, int wc, int fr, int fq) const {
;         const int row0 = u.pm * BM + wr * 64 + fr, col0 = u.pn * BM + wc * 32 + 4 * fq;
; #pragma unroll
;         for (int ai = 0; ai < 2; ++ai) {
;             f32x4 res[4][2][2];
; #pragma unroll
;             for (int m = 0; m < 4; ++m) { const size_t off = (size_t)(row0 + ai * HALF + m * 16) * ldc + col0;
; template <class Epi, class Sched, bool ALIGN_EPI = false, bool SP2 = false>
; __device__ __forceinline__ void gemm_phase(PG8_LAS unsigned char* lds, const Gemm g, const Sched& S, const Epi& E) {
;     ...
;         for (int t = 0; t < nt; t += 2) {
;             const bool last = (t == nt - 2);
;             const char* a1 = cA + (size_t)(t + 1) * kstep;
;             const char* a2 = last ? nA : cA + (size_t)(t + 2) * kstep; const char* b2 = last ? nB : cB + (size_t)(t + 2) * kstep;
;             const char* a3 = a2 + kstep; const char* b3 = b2 + kstep;
;             if (last && has_next) S.a_ready(nxt);
;             if constexpr (SP2) {
;             PG8_LDB(B0, 0, 0); PG8_LDB(B1, 0, 1); PG8_SCHED; PG8_LDA(At, 0, 0); PG8_STAGE(PG8_SA(1, 1), a1 + hstep, voffA);
.Lp3_k2_entry:
	s_mov_b32 s101, 2
	v_readlane_b32 s84, v254, 0
	v_readlane_b32 s85, v254, 1
	v_lshrrev_b32_e32 v250, 8, v229
	v_lshlrev_b32_e32 v250, 6, v250
	v_and_b32_e32 v251, 15, v229
	v_or_b32_e32 v250, v250, v251
	v_lshl_add_u32 v250, s24, 8, v250
	v_bfe_u32 v251, v229, 6, 2
	v_lshlrev_b32_e32 v251, 5, v251
	v_bfe_u32 v252, v229, 4, 2
	v_lshl_or_b32 v251, v252, 2, v251
	v_lshl_add_u32 v251, s45, 8, v251
	v_lshlrev_b32_e32 v250, 13, v250
	v_lshl_add_u32 v250, v251, 2, v250
.Lp3_k2:
	ds_read_b128 v[140:143], v149
	ds_read_b128 v[152:155], v149 offset:1024
	ds_read_b128 v[156:159], v149 offset:2048
	ds_read_b128 v[160:163], v149 offset:3072
	ds_read_b128 v[164:167], v150
	ds_read_b128 v[168:171], v150 offset:1024
	ds_read_b128 v[172:175], v150 offset:2048
	ds_read_b128 v[176:179], v150 offset:3072
	s_add_u32 s28, s26, 0xfff80080
	s_addc_u32 s29, s27, -1
	s_cmp_eq_u32 s49, 28
	s_cselect_b32 s35, s19, s29
	s_cselect_b32 s34, s31, s28
	s_cselect_b32 s29, s17, s48
	s_cselect_b32 s28, s46, s47
	v_lshl_add_u64 v[144:145], s[26:27], 0, v[132:133]
	s_add_i32 m0, s25, 0xc000
	ds_read_b128 v[180:183], v151
	ds_read_b128 v[184:187], v151 offset:1024
	ds_read_b128 v[188:191], v151 offset:2048
	ds_read_b128 v[192:195], v151 offset:3072
	ds_read_b128 v[196:199], v151 offset:4096
	ds_read_b128 v[200:203], v151 offset:5120
	ds_read_b128 v[204:207], v151 offset:6144
	ds_read_b128 v[208:211], v151 offset:7168
	global_load_lds_dwordx4 v[144:145], off
	v_lshl_add_u64 v[144:145], s[26:27], 0, v[134:135]
	s_add_i32 m0, s25, 0xe000
	s_nop 0
	global_load_lds_dwordx4 v[144:145], off
	s_waitcnt vmcnt(8)
	s_add_i32 s86, s49, 2
	s_cmp_ge_u32 s86, 16
	s_cbranch_scc1 .Lsbt_8_16
	s_cmp_ge_u32 s86, 8
	s_cbranch_scc1 .Lsbt_4_8
	s_cmp_ge_u32 s86, 4
	s_cbranch_scc1 .Lsbt_2_4
	s_cmp_ge_u32 s86, 2
	s_cbranch_scc1 .Lsbt_1_2
	s_branch .Lsb_0
.Lsbt_1_2:
	s_branch .Lsb_1
.Lsbt_2_4:
	s_cmp_ge_u32 s86, 6
	s_cbranch_scc1 .Lsbt_3_4
	s_branch .Lsb_2

;     __device__ __forceinline__ void operator()(const f32x4 (&acc)[2][2][4][2], const Unit& u, int wr, int wc, int fr, int fq) const {
;     ...
;             for (int m = 0; m < 4; ++m) { const size_t off = (size_t)(row0 + ai * HALF + m * 16) * ldc + col0;
; #pragma unroll
;                 for (int bj = 0; bj < 2; ++bj)
; #pragma unroll
;                     for (int n = 0; n < 2; ++n) res[m][bj][n] = *(const f32x4*)(base + off + bj * HALF + n * 16); }
.Lsbt_4_8:
	s_cmp_ge_u32 s86, 12
	s_cbranch_scc1 .Lsbt_6_8
	s_cmp_ge_u32 s86, 10
	s_cbranch_scc1 .Lsbt_5_6
	s_branch .Lsb_4

;     __device__ __forceinline__ void operator()(const f32x4 (&acc)[2][2][4][2], const Unit& u, int wr, int wc, int fr, int fq) const {
;     ...
;             for (int m = 0; m < 4; ++m) { const size_t off = (size_t)(row0 + ai * HALF + m * 16) * ldc + col0;
; #pragma unroll
;                 for (int bj = 0; bj < 2; ++bj)
; #pragma unroll
;                     for (int n = 0; n < 2; ++n) res[m][bj][n] = *(const f32x4*)(base + off + bj * HALF + n * 16); }
.Lsbt_6_8:
	s_cmp_ge_u32 s86, 14
	s_cbranch_scc1 .Lsbt_7_8
	s_branch .Lsb_6

;     __device__ __forceinline__ void operator()(const f32x4 (&acc)[2][2][4][2], const Unit& u, int wr, int wc, int fr, int fq) const {
;     ...
;             for (int m = 0; m < 4; ++m) { const size_t off = (size_t)(row0 + ai * HALF + m * 16) * ldc + col0;
; #pragma unroll
;                 for (int bj = 0; bj < 2; ++bj)
; #pragma unroll
;                     for (int n = 0; n < 2; ++n) res[m][bj][n] = *(const f32x4*)(base + off + bj * HALF + n * 16); }
.Lsbt_8_16:
	s_cmp_ge_u32 s86, 24
	s_cbranch_scc1 .Lsbt_12_16
	s_cmp_ge_u32 s86, 20
	s_cbranch_scc1 .Lsbt_10_12
	s_cmp_ge_u32 s86, 18
	s_cbranch_scc1 .Lsbt_9_10
	s_branch .Lsb_8

;     __device__ __forceinline__ void operator()(const f32x4 (&acc)[2][2][4][2], const Unit& u, int wr, int wc, int fr, int fq) const {
;     ...
;             for (int m = 0; m < 4; ++m) { const size_t off = (size_t)(row0 + ai * HALF + m * 16) * ldc + col0;
; #pragma unroll
;                 for (int bj = 0; bj < 2; ++bj)
; #pragma unroll
;                     for (int n = 0; n < 2; ++n) res[m][bj][n] = *(const f32x4*)(base + off + bj * HALF + n * 16); }
.Lsbt_10_12:
	s_cmp_ge_u32 s86, 22
	s_cbranch_scc1 .Lsbt_11_12
	s_branch .Lsb_10

;     __device__ __forceinline__ void operator()(const f32x4 (&acc)[2][2][4][2], const Unit& u, int wr, int wc, int fr, int fq) const {
;     ...
;             for (int m = 0; m < 4; ++m) { const size_t off = (size_t)(row0 + ai * HALF + m * 16) * ldc + col0;
; #pragma unroll
;                 for (int bj = 0; bj < 2; ++bj)
; #pragma unroll
;                     for (int n = 0; n < 2; ++n) res[m][bj][n] = *(const f32x4*)(base + off + bj * HALF + n * 16); }
.Lsbt_12_16:
	s_cmp_ge_u32 s86, 28
	s_cbranch_scc1 .Lsbt_14_16
	s_cmp_ge_u32 s86, 26
	s_cbranch_scc1 .Lsbt_13_14
	s_branch .Lsb_12

;     __device__ __forceinline__ void operator()(const f32x4 (&acc)[2][2][4][2], const Unit& u, int wr, int wc, int fr, int fq) const {
;     ...
;             for (int m = 0; m < 4; ++m) { const size_t off = (size_t)(row0 + ai * HALF + m * 16) * ldc + col0;
; #pragma unroll
;                 for (int bj = 0; bj < 2; ++bj)
; #pragma unroll
;                     for (int n = 0; n < 2; ++n) res[m][bj][n] = *(const f32x4*)(base + off + bj * HALF + n * 16); }
.Lsbt_14_16:
	s_cmp_ge_u32 s86, 30
	s_cbranch_scc1 .Lsbt_15_16
	s_branch .Lsb_14

;     __device__ __forceinline__ void operator()(const f32x4 (&acc)[2][2][4][2], const Unit& u, int wr, int wc, int fr, int fq) const {
;     ...
;             for (int m = 0; m < 4; ++m) { const size_t off = (size_t)(row0 + ai * HALF + m * 16) * ldc + col0;
; #pragma unroll
;                 for (int bj = 0; bj < 2; ++bj)
; #pragma unroll
;                     for (int n = 0; n < 2; ++n) res[m][bj][n] = *(const f32x4*)(base + off + bj * HALF + n * 16); }
;             asm volatile("" ::: "memory");
; #pragma unroll
;             for (int m = 0; m < 4; ++m) { const size_t off = (size_t)(row0 + ai * HALF + m * 16) * ldc + col0;
; #pragma unroll
;                 for (int bj = 0; bj < 2; ++bj)
; #pragma unroll
;                     for (int n = 0; n < 2; ++n) *(f32x4*)(out + off + bj * HALF + n * 16) = res[m][bj][n] + acc[ai][bj][m][n]; }
.Lsb_0:
	global_load_dwordx4 v[232:235], v250, s[84:85]
	global_load_dwordx4 v[236:239], v250, s[84:85] offset:64
	s_branch .Lsb_ret
.Lsb_1:
	v_pk_add_f32 v[124:125], v[124:125], v[232:233]
	v_pk_add_f32 v[126:127], v[126:127], v[234:235]
	v_pk_add_f32 v[120:121], v[120:121], v[236:237]
	v_pk_add_f32 v[122:123], v[122:123], v[238:239]
	global_load_dwordx4 v[240:243], v250, s[84:85] offset:512
	global_load_dwordx4 v[244:247], v250, s[84:85] offset:576
	s_branch .Lsb_ret
.Lsb_2:
	v_pk_add_f32 v[104:105], v[104:105], v[240:241]
	v_pk_add_f32 v[106:107], v[106:107], v[242:243]
	v_pk_add_f32 v[96:97], v[96:97], v[244:245]
	v_pk_add_f32 v[98:99], v[98:99], v[246:247]
	s_add_u32 s86, s84, 0x20000
	s_addc_u32 s87, s85, 0
	global_load_dwordx4 v[232:235], v250, s[86:87]
	global_load_dwordx4 v[236:239], v250, s[86:87] offset:64
	s_branch .Lsb_ret
.Lsb_3:
	v_pk_add_f32 v[116:117], v[116:117], v[232:233]
	v_pk_add_f32 v[118:119], v[118:119], v[234:235]
	v_pk_add_f32 v[112:113], v[112:113], v[236:237]
	v_pk_add_f32 v[114:115], v[114:115], v[238:239]
	s_add_u32 s86, s84, 0x20000
	s_addc_u32 s87, s85, 0
	global_load_dwordx4 v[240:243], v250, s[86:87] offset:512
	global_load_dwordx4 v[244:247], v250, s[86:87] offset:576
	s_branch .Lsb_ret
.Lsb_4:
	v_pk_add_f32 v[88:89], v[88:89], v[240:241]
	v_pk_add_f32 v[90:91], v[90:91], v[242:243]
	v_pk_add_f32 v[84:85], v[84:85], v[244:245]
	v_pk_add_f32 v[86:87], v[86:87], v[246:247]
	s_add_u32 s86, s84, 0x40000
	s_addc_u32 s87, s85, 0
	global_load_dwordx4 v[232:235], v250, s[86:87]
	global_load_dwordx4 v[236:239], v250, s[86:87] offset:64
	s_branch .Lsb_ret
.Lsb_5:
	v_pk_add_f32 v[108:109], v[108:109], v[232:233]
	v_pk_add_f32 v[110:111], v[110:111], v[234:235]
	v_pk_add_f32 v[100:101], v[100:101], v[236:237]
	v_pk_add_f32 v[102:103], v[102:103], v[238:239]
	s_add_u32 s86, s84, 0x40000
	s_addc_u32 s87, s85, 0
	global_load_dwordx4 v[240:243], v250, s[86:87] offset:512
	global_load_dwordx4 v[244:247], v250, s[86:87] offset:576
	s_branch .Lsb_ret
.Lsb_6:
	v_pk_add_f32 v[76:77], v[76:77], v[240:241]
	v_pk_add_f32 v[78:79], v[78:79], v[242:243]
	v_pk_add_f32 v[72:73], v[72:73], v[244:245]
	v_pk_add_f32 v[74:75], v[74:75], v[246:247]
	s_add_u32 s86, s84, 0x60000
	s_addc_u32 s87, s85, 0
	global_load_dwordx4 v[232:235], v250, s[86:87]
	global_load_dwordx4 v[236:239], v250, s[86:87] offset:64
	s_branch .Lsb_ret
.Lsb_7:
	v_pk_add_f32 v[92:93], v[92:93], v[232:233]
	v_pk_add_f32 v[94:95], v[94:95], v[234:235]
	v_pk_add_f32 v[80:81], v[80:81], v[236:237]
	v_pk_add_f32 v[82:83], v[82:83], v[238:239]
	s_add_u32 s86, s84, 0x60000
	s_addc_u32 s87, s85, 0
	global_load_dwordx4 v[240:243], v250, s[86:87] offset:512
	global_load_dwordx4 v[244:247], v250, s[86:87] offset:576
	s_branch .Lsb_ret
.Lsb_8:
	v_pk_add_f32 v[68:69], v[68:69], v[240:241]
	v_pk_add_f32 v[70:71], v[70:71], v[242:243]
	v_pk_add_f32 v[64:65], v[64:65], v[244:245]
	v_pk_add_f32 v[66:67], v[66:67], v[246:247]
	s_add_u32 s86, s84, 0x100000
	s_addc_u32 s87, s85, 0
	global_load_dwordx4 v[232:235], v250, s[86:87]
	global_load_dwordx4 v[236:239], v250, s[86:87] offset:64
	s_branch .Lsb_ret
.Lsb_9:
	v_pk_add_f32 v[60:61], v[60:61], v[232:233]
	v_pk_add_f32 v[62:63], v[62:63], v[234:235]
	v_pk_add_f32 v[56:57], v[56:57], v[236:237]
	v_pk_add_f32 v[58:59], v[58:59], v[238:239]
	s_add_u32 s86, s84, 0x100000
	s_addc_u32 s87, s85, 0
	global_load_dwordx4 v[240:243], v250, s[86:87] offset:512
	global_load_dwordx4 v[244:247], v250, s[86:87] offset:576
	s_branch .Lsb_ret
.Lsb_10:
	v_pk_add_f32 v[40:41], v[40:41], v[240:241]
	v_pk_add_f32 v[42:43], v[42:43], v[242:243]
	v_pk_add_f32 v[32:33], v[32:33], v[244:245]
	v_pk_add_f32 v[34:35], v[34:35], v[246:247]
	s_add_u32 s86, s84, 0x120000
	s_addc_u32 s87, s85, 0
	global_load_dwordx4 v[232:235], v250, s[86:87]
	global_load_dwordx4 v[236:239], v250, s[86:87] offset:64
	s_branch .Lsb_ret
.Lsb_11:
	v_pk_add_f32 v[52:53], v[52:53], v[232:233]
	v_pk_add_f32 v[54:55], v[54:55], v[234:235]
	v_pk_add_f32 v[48:49], v[48:49], v[236:237]
	v_pk_add_f32 v[50:51], v[50:51], v[238:239]
	s_add_u32 s86, s84, 0x120000
	s_addc_u32 s87, s85, 0
	global_load_dwordx4 v[240:243], v250, s[86:87] offset:512
	global_load_dwordx4 v[244:247], v250, s[86:87] offset:576
	s_branch .Lsb_ret
.Lsb_12:
	v_pk_add_f32 v[24:25], v[24:25], v[240:241]
	v_pk_add_f32 v[26:27], v[26:27], v[242:243]
	v_pk_add_f32 v[20:21], v[20:21], v[244:245]
	v_pk_add_f32 v[22:23], v[22:23], v[246:247]
	s_add_u32 s86, s84, 0x140000
	s_addc_u32 s87, s85, 0
	global_load_dwordx4 v[232:235], v250, s[86:87]
	global_load_dwordx4 v[236:239], v250, s[86:87] offset:64
	s_branch .Lsb_ret
.Lsb_13:
	v_pk_add_f32 v[44:45], v[44:45], v[232:233]
	v_pk_add_f32 v[46:47], v[46:47], v[234:235]
	v_pk_add_f32 v[36:37], v[36:37], v[236:237]
	v_pk_add_f32 v[38:39], v[38:39], v[238:239]
	s_add_u32 s86, s84, 0x140000
	s_addc_u32 s87, s85, 0
	global_load_dwordx4 v[240:243], v250, s[86:87] offset:512
	global_load_dwordx4 v[244:247], v250, s[86:87] offset:576
	s_branch .Lsb_ret
.Lsb_14:
	v_pk_add_f32 v[12:13], v[12:13], v[240:241]
	v_pk_add_f32 v[14:15], v[14:15], v[242:243]
	v_pk_add_f32 v[8:9], v[8:9], v[244:245]
	v_pk_add_f32 v[10:11], v[10:11], v[246:247]
	s_add_u32 s86, s84, 0x160000
	s_addc_u32 s87, s85, 0
	global_load_dwordx4 v[232:235], v250, s[86:87]
	global_load_dwordx4 v[236:239], v250, s[86:87] offset:64
	s_branch .Lsb_ret
.Lsb_15:
	v_pk_add_f32 v[28:29], v[28:29], v[232:233]
	v_pk_add_f32 v[30:31], v[30:31], v[234:235]
	v_pk_add_f32 v[16:17], v[16:17], v[236:237]
	v_pk_add_f32 v[18:19], v[18:19], v[238:239]
	s_add_u32 s86, s84, 0x160000
	s_addc_u32 s87, s85, 0
	global_load_dwordx4 v[240:243], v250, s[86:87] offset:512
	global_load_dwordx4 v[244:247], v250, s[86:87] offset:576
; #define PG8_STAGE(bufoff, gbase, voff) do { _Pragma("unroll") for (int _i = 0; _i < 2; ++_i) \
;         __builtin_amdgcn_global_load_lds((const unsigned*)((const char*)(gbase) + (voff)[_i]), (PG8_LAS unsigned*)(lds + (bufoff) + ldsw + _i * 8192), 16, 0, 0); } while (0)
; #define PG8_LDA(dst, b, h) do { _Pragma("unroll") for (int m = 0; m < 4; ++m) _Pragma("unroll") for (int k = 0; k < 2; ++k) dst[m][k] = *(const PG8_LAS bf16x8*)(lds + PG8_SA(b, h) + aoff + m * 2048 + k * 1024); } while (0)
; #define PG8_MMA(ai, bj, At, Bt) do { __builtin_amdgcn_s_setprio(1); _Pragma("unroll") for (int m = 0; m < 4; ++m) _Pragma("unroll") for (int n = 0; n < 2; ++n) _Pragma("unroll") for (int k = 0; k < 2; ++k) \
;         acc[ai][bj][m][n] = __builtin_amdgcn_mfma_f32_16x16x32_bf16(Bt[n][k], At[m][k], acc[ai][bj][m][n], 0, 0, 0); __builtin_amdgcn_s_setprio(0); } while (0)
; #define PG8_WAIT_V(n) asm volatile("s_waitcnt vmcnt(" #n ")" ::: "memory")
; #define PG8_WAIT_L(n) asm volatile("s_waitcnt lgkmcnt(" #n ")" ::: "memory")
; #define PG8_BAR __builtin_amdgcn_s_barrier()
; #define PG8_SCHED __builtin_amdgcn_sched_barrier(0)
; template <class Epi, class Sched, bool ALIGN_EPI = false, bool SP2 = false>
; __device__ __forceinline__ void gemm_phase(PG8_LAS unsigned char* lds, const Gemm g, const Sched& S, const Epi& E) {
;     ...
;             PG8_WAIT_V(8); PG8_WAIT_L(0); PG8_BAR; PG8_MMA(0, 0, At, B0); PG8_MMA(0, 1, At, B1); PG8_BAR; PG8_SCHED;
;             PG8_LDA(At, 0, 1); PG8_STAGE(PG8_SB(0, 0), b2, voffB); PG8_STAGE(PG8_SB(0, 1), b2 + hstep, voffB); PG8_STAGE(PG8_SA(0, 0), a2, voffA);
;             PG8_WAIT_V(8); PG8_WAIT_L(0); PG8_BAR; PG8_MMA(1, 0, At, B0); PG8_MMA(1, 1, At, B1); PG8_BAR; PG8_SCHED;
.Lsb_ret:
	s_waitcnt lgkmcnt(0)
	s_barrier
	s_setprio 1
	s_waitcnt lgkmcnt(0)
	v_mfma_f32_16x16x32_bf16 v[124:127], v[140:143], v[180:183], v[124:127]
	v_mfma_f32_16x16x32_bf16 v[124:127], v[152:155], v[184:187], v[124:127]
	v_mfma_f32_16x16x32_bf16 v[116:119], v[152:155], v[192:195], v[116:119]
	v_mfma_f32_16x16x32_bf16 v[116:119], v[140:143], v[188:191], v[116:119]
	v_mfma_f32_16x16x32_bf16 v[108:111], v[140:143], v[196:199], v[108:111]
	v_mfma_f32_16x16x32_bf16 v[108:111], v[152:155], v[200:203], v[108:111]
	v_mfma_f32_16x16x32_bf16 v[92:95], v[152:155], v[208:211], v[92:95]
	v_mfma_f32_16x16x32_bf16 v[92:95], v[140:143], v[204:207], v[92:95]
	v_mfma_f32_16x16x32_bf16 v[80:83], v[156:159], v[204:207], v[80:83]
	v_mfma_f32_16x16x32_bf16 v[80:83], v[160:163], v[208:211], v[80:83]
	v_mfma_f32_16x16x32_bf16 v[100:103], v[160:163], v[200:203], v[100:103]
	v_mfma_f32_16x16x32_bf16 v[100:103], v[156:159], v[196:199], v[100:103]
	v_mfma_f32_16x16x32_bf16 v[112:115], v[156:159], v[188:191], v[112:115]
	v_mfma_f32_16x16x32_bf16 v[112:115], v[160:163], v[192:195], v[112:115]
	v_mfma_f32_16x16x32_bf16 v[120:123], v[160:163], v[184:187], v[120:123]
	v_mfma_f32_16x16x32_bf16 v[120:123], v[156:159], v[180:183], v[120:123]
	s_setprio 0
	s_setprio 1
	v_mfma_f32_16x16x32_bf16 v[104:107], v[164:167], v[180:183], v[104:107]
	v_mfma_f32_16x16x32_bf16 v[104:107], v[168:171], v[184:187], v[104:107]
	v_mfma_f32_16x16x32_bf16 v[88:91], v[168:171], v[192:195], v[88:91]
	v_mfma_f32_16x16x32_bf16 v[88:91], v[164:167], v[188:191], v[88:91]
	v_mfma_f32_16x16x32_bf16 v[76:79], v[164:167], v[196:199], v[76:79]
	v_mfma_f32_16x16x32_bf16 v[76:79], v[168:171], v[200:203], v[76:79]
	v_mfma_f32_16x16x32_bf16 v[68:71], v[168:171], v[208:211], v[68:71]
	v_mfma_f32_16x16x32_bf16 v[68:71], v[164:167], v[204:207], v[68:71]
	v_mfma_f32_16x16x32_bf16 v[64:67], v[172:175], v[204:207], v[64:67]
	v_mfma_f32_16x16x32_bf16 v[64:67], v[176:179], v[208:211], v[64:67]
	v_mfma_f32_16x16x32_bf16 v[72:75], v[176:179], v[200:203], v[72:75]
	v_mfma_f32_16x16x32_bf16 v[72:75], v[172:175], v[196:199], v[72:75]
	v_mfma_f32_16x16x32_bf16 v[84:87], v[172:175], v[188:191], v[84:87]
	v_mfma_f32_16x16x32_bf16 v[84:87], v[176:179], v[192:195], v[84:87]
	v_mfma_f32_16x16x32_bf16 v[96:99], v[176:179], v[184:187], v[96:99]
	v_mfma_f32_16x16x32_bf16 v[96:99], v[172:175], v[180:183], v[96:99]
	s_setprio 0
	s_barrier
	s_add_i32 s50, s43, s30
	v_lshl_add_u64 v[144:145], s[28:29], 0, v[128:129]
	s_mov_b32 m0, s50
	ds_read_b128 v[180:183], v151 offset:16384
	ds_read_b128 v[184:187], v151 offset:17408
	ds_read_b128 v[188:191], v151 offset:18432
	ds_read_b128 v[192:195], v151 offset:19456
	ds_read_b128 v[196:199], v151 offset:20480
	ds_read_b128 v[200:203], v151 offset:21504
	ds_read_b128 v[204:207], v151 offset:22528
	ds_read_b128 v[208:211], v151 offset:23552
	global_load_lds_dwordx4 v[144:145], off
	s_add_i32 m0, s50, 0x2000
	s_add_u32 s50, s28, 0x80000
	v_lshl_add_u64 v[212:213], s[28:29], 0, v[130:131]
	s_addc_u32 s51, s29, 0
	s_add_i32 s52, s44, s30
	global_load_lds_dwordx4 v[212:213], off
	v_lshl_add_u64 v[214:215], s[50:51], 0, v[128:129]
	s_mov_b32 m0, s52
	v_lshl_add_u64 v[216:217], s[34:35], 0, v[130:131]
	global_load_lds_dwordx4 v[214:215], off
	v_lshl_add_u64 v[214:215], s[50:51], 0, v[130:131]
	s_add_i32 m0, s52, 0x2000
	s_nop 0
	global_load_lds_dwordx4 v[214:215], off
	v_lshl_add_u64 v[214:215], s[34:35], 0, v[128:129]
	s_mov_b32 m0, s25
	s_nop 0
	global_load_lds_dwordx4 v[214:215], off
	s_mov_b32 m0, s36
	s_nop 0
	global_load_lds_dwordx4 v[216:217], off
	s_waitcnt vmcnt(10)
	s_waitcnt lgkmcnt(0)
	s_barrier
	s_setprio 1
	s_waitcnt lgkmcnt(0)
	v_mfma_f32_16x16x32_bf16 v[60:63], v[140:143], v[180:183], v[60:63]
	v_mfma_f32_16x16x32_bf16 v[60:63], v[152:155], v[184:187], v[60:63]
	v_mfma_f32_16x16x32_bf16 v[52:55], v[152:155], v[192:195], v[52:55]
	v_mfma_f32_16x16x32_bf16 v[52:55], v[140:143], v[188:191], v[52:55]
	v_mfma_f32_16x16x32_bf16 v[44:47], v[140:143], v[196:199], v[44:47]
	v_mfma_f32_16x16x32_bf16 v[44:47], v[152:155], v[200:203], v[44:47]
	v_mfma_f32_16x16x32_bf16 v[28:31], v[152:155], v[208:211], v[28:31]
	v_mfma_f32_16x16x32_bf16 v[28:31], v[140:143], v[204:207], v[28:31]
	v_mfma_f32_16x16x32_bf16 v[16:19], v[156:159], v[204:207], v[16:19]
	v_mfma_f32_16x16x32_bf16 v[16:19], v[160:163], v[208:211], v[16:19]
	v_mfma_f32_16x16x32_bf16 v[36:39], v[160:163], v[200:203], v[36:39]
	v_mfma_f32_16x16x32_bf16 v[36:39], v[156:159], v[196:199], v[36:39]
	v_mfma_f32_16x16x32_bf16 v[48:51], v[156:159], v[188:191], v[48:51]
	v_mfma_f32_16x16x32_bf16 v[48:51], v[160:163], v[192:195], v[48:51]
	v_mfma_f32_16x16x32_bf16 v[56:59], v[160:163], v[184:187], v[56:59]
	v_mfma_f32_16x16x32_bf16 v[56:59], v[156:159], v[180:183], v[56:59]
	s_setprio 0
	s_setprio 1
	v_mfma_f32_16x16x32_bf16 v[40:43], v[164:167], v[180:183], v[40:43]
	v_mfma_f32_16x16x32_bf16 v[40:43], v[168:171], v[184:187], v[40:43]
	v_mfma_f32_16x16x32_bf16 v[24:27], v[168:171], v[192:195], v[24:27]
	v_mfma_f32_16x16x32_bf16 v[24:27], v[164:167], v[188:191], v[24:27]
	v_mfma_f32_16x16x32_bf16 v[12:15], v[164:167], v[196:199], v[12:15]
	v_mfma_f32_16x16x32_bf16 v[12:15], v[168:171], v[200:203], v[12:15]
	v_mfma_f32_16x16x32_bf16 v[4:7], v[168:171], v[208:211], v[4:7]
	v_mfma_f32_16x16x32_bf16 v[4:7], v[164:167], v[204:207], v[4:7]
	v_mfma_f32_16x16x32_bf16 v[0:3], v[172:175], v[204:207], v[0:3]
	v_mfma_f32_16x16x32_bf16 v[0:3], v[176:179], v[208:211], v[0:3]
	v_mfma_f32_16x16x32_bf16 v[8:11], v[176:179], v[200:203], v[8:11]
	v_mfma_f32_16x16x32_bf16 v[8:11], v[172:175], v[196:199], v[8:11]
	v_mfma_f32_16x16x32_bf16 v[20:23], v[172:175], v[188:191], v[20:23]
	v_mfma_f32_16x16x32_bf16 v[20:23], v[176:179], v[192:195], v[20:23]
	v_mfma_f32_16x16x32_bf16 v[32:35], v[176:179], v[184:187], v[32:35]
	v_mfma_f32_16x16x32_bf16 v[32:35], v[172:175], v[180:183], v[32:35]
	s_setprio 0
	s_barrier
; #define PG8_STAGE(bufoff, gbase, voff) do { _Pragma("unroll") for (int _i = 0; _i < 2; ++_i) \
;         __builtin_amdgcn_global_load_lds((const unsigned*)((const char*)(gbase) + (voff)[_i]), (PG8_LAS unsigned*)(lds + (bufoff) + ldsw + _i * 8192), 16, 0, 0); } while (0)
; #define PG8_LDA(dst, b, h) do { _Pragma("unroll") for (int m = 0; m < 4; ++m) _Pragma("unroll") for (int k = 0; k < 2; ++k) dst[m][k] = *(const PG8_LAS bf16x8*)(lds + PG8_SA(b, h) + aoff + m * 2048 + k * 1024); } while (0)
; #define PG8_LDB(dst, b, h) do { _Pragma("unroll") for (int n = 0; n < 2; ++n) _Pragma("unroll") for (int k = 0; k < 2; ++k) dst[n][k] = *(const PG8_LAS bf16x8*)(lds + PG8_SB(b, h) + boff + n * 2048 + k * 1024); } while (0)
; #define PG8_MMA(ai, bj, At, Bt) do { __builtin_amdgcn_s_setprio(1); _Pragma("unroll") for (int m = 0; m < 4; ++m) _Pragma("unroll") for (int n = 0; n < 2; ++n) _Pragma("unroll") for (int k = 0; k < 2; ++k) \
;         acc[ai][bj][m][n] = __builtin_amdgcn_mfma_f32_16x16x32_bf16(Bt[n][k], At[m][k], acc[ai][bj][m][n], 0, 0, 0); __builtin_amdgcn_s_setprio(0); } while (0)
; #define PG8_WAIT_V(n) asm volatile("s_waitcnt vmcnt(" #n ")" ::: "memory")
; #define PG8_WAIT_L(n) asm volatile("s_waitcnt lgkmcnt(" #n ")" ::: "memory")
; #define PG8_BAR __builtin_amdgcn_s_barrier()
; #define PG8_SCHED __builtin_amdgcn_sched_barrier(0)
; template <class Epi, class Sched, bool ALIGN_EPI = false, bool SP2 = false>
; __device__ __forceinline__ void gemm_phase(PG8_LAS unsigned char* lds, const Gemm g, const Sched& S, const Epi& E) {
;     ...
;             PG8_LDB(B0, 1, 0); PG8_LDB(B1, 1, 1); PG8_SCHED; PG8_LDA(At, 1, 0); PG8_STAGE(PG8_SA(0, 1), a2 + hstep, voffA);
;             PG8_WAIT_V(8); PG8_WAIT_L(0); PG8_BAR; PG8_MMA(0, 0, At, B0); PG8_MMA(0, 1, At, B1); PG8_BAR; PG8_SCHED;
	s_add_i32 s50, 0, 0x18000
	s_add_i32 s51, 0, 0x1c000
	v_add_u32_e32 v160, s50, v147
	v_add_u32_e32 v176, s51, v147
	ds_read_b128 v[140:143], v160
	ds_read_b128 v[152:155], v160 offset:1024
	ds_read_b128 v[156:159], v160 offset:2048
	ds_read_b128 v[160:163], v160 offset:3072
	ds_read_b128 v[164:167], v176
	ds_read_b128 v[168:171], v176 offset:1024
	ds_read_b128 v[172:175], v176 offset:2048
	ds_read_b128 v[176:179], v176 offset:3072
	s_add_u32 s34, s34, 0x80000
	s_addc_u32 s35, s35, 0
	s_mov_b32 m0, s37
	v_lshl_add_u64 v[218:219], s[34:35], 0, v[128:129]
	ds_read_b128 v[180:183], v151 offset:32768
	ds_read_b128 v[184:187], v151 offset:33792
	ds_read_b128 v[188:191], v151 offset:34816
	ds_read_b128 v[192:195], v151 offset:35840
	ds_read_b128 v[196:199], v151 offset:36864
	ds_read_b128 v[200:203], v151 offset:37888
	ds_read_b128 v[204:207], v151 offset:38912
	ds_read_b128 v[208:211], v151 offset:39936
	global_load_lds_dwordx4 v[218:219], off
	v_lshl_add_u64 v[218:219], s[34:35], 0, v[130:131]
	s_mov_b32 m0, s38
	s_nop 0
	global_load_lds_dwordx4 v[218:219], off
	s_waitcnt vmcnt(10)
	s_waitcnt lgkmcnt(0)
	s_barrier
	s_setprio 1
	s_waitcnt lgkmcnt(0)
	v_mfma_f32_16x16x32_bf16 v[124:127], v[140:143], v[180:183], v[124:127]
	v_mfma_f32_16x16x32_bf16 v[124:127], v[152:155], v[184:187], v[124:127]
	v_mfma_f32_16x16x32_bf16 v[116:119], v[152:155], v[192:195], v[116:119]
	v_mfma_f32_16x16x32_bf16 v[116:119], v[140:143], v[188:191], v[116:119]
	v_mfma_f32_16x16x32_bf16 v[108:111], v[140:143], v[196:199], v[108:111]
	v_mfma_f32_16x16x32_bf16 v[108:111], v[152:155], v[200:203], v[108:111]
	v_mfma_f32_16x16x32_bf16 v[92:95], v[152:155], v[208:211], v[92:95]
	v_mfma_f32_16x16x32_bf16 v[92:95], v[140:143], v[204:207], v[92:95]
	v_mfma_f32_16x16x32_bf16 v[80:83], v[156:159], v[204:207], v[80:83]
	v_mfma_f32_16x16x32_bf16 v[80:83], v[160:163], v[208:211], v[80:83]
	v_mfma_f32_16x16x32_bf16 v[100:103], v[160:163], v[200:203], v[100:103]
	v_mfma_f32_16x16x32_bf16 v[100:103], v[156:159], v[196:199], v[100:103]
	v_mfma_f32_16x16x32_bf16 v[112:115], v[156:159], v[188:191], v[112:115]
	v_mfma_f32_16x16x32_bf16 v[112:115], v[160:163], v[192:195], v[112:115]
	v_mfma_f32_16x16x32_bf16 v[120:123], v[160:163], v[184:187], v[120:123]
	v_mfma_f32_16x16x32_bf16 v[120:123], v[156:159], v[180:183], v[120:123]
	s_setprio 0
	s_setprio 1
	v_mfma_f32_16x16x32_bf16 v[104:107], v[164:167], v[180:183], v[104:107]
	v_mfma_f32_16x16x32_bf16 v[104:107], v[168:171], v[184:187], v[104:107]
	v_mfma_f32_16x16x32_bf16 v[88:91], v[168:171], v[192:195], v[88:91]
	v_mfma_f32_16x16x32_bf16 v[88:91], v[164:167], v[188:191], v[88:91]
	v_mfma_f32_16x16x32_bf16 v[76:79], v[164:167], v[196:199], v[76:79]
	v_mfma_f32_16x16x32_bf16 v[76:79], v[168:171], v[200:203], v[76:79]
	v_mfma_f32_16x16x32_bf16 v[68:71], v[168:171], v[208:211], v[68:71]
	v_mfma_f32_16x16x32_bf16 v[68:71], v[164:167], v[204:207], v[68:71]
	v_mfma_f32_16x16x32_bf16 v[64:67], v[172:175], v[204:207], v[64:67]
	v_mfma_f32_16x16x32_bf16 v[64:67], v[176:179], v[208:211], v[64:67]
	v_mfma_f32_16x16x32_bf16 v[72:75], v[176:179], v[200:203], v[72:75]
	v_mfma_f32_16x16x32_bf16 v[72:75], v[172:175], v[196:199], v[72:75]
	v_mfma_f32_16x16x32_bf16 v[84:87], v[172:175], v[188:191], v[84:87]
	v_mfma_f32_16x16x32_bf16 v[84:87], v[176:179], v[192:195], v[84:87]
	v_mfma_f32_16x16x32_bf16 v[96:99], v[176:179], v[184:187], v[96:99]
	v_mfma_f32_16x16x32_bf16 v[96:99], v[172:175], v[180:183], v[96:99]
	s_setprio 0
	s_barrier
; #define PG8_STAGE(bufoff, gbase, voff) do { _Pragma("unroll") for (int _i = 0; _i < 2; ++_i) \
;         __builtin_amdgcn_global_load_lds((const unsigned*)((const char*)(gbase) + (voff)[_i]), (PG8_LAS unsigned*)(lds + (bufoff) + ldsw + _i * 8192), 16, 0, 0); } while (0)
; #define PG8_LDA(dst, b, h) do { _Pragma("unroll") for (int m = 0; m < 4; ++m) _Pragma("unroll") for (int k = 0; k < 2; ++k) dst[m][k] = *(const PG8_LAS bf16x8*)(lds + PG8_SA(b, h) + aoff + m * 2048 + k * 1024); } while (0)
; #define PG8_MMA(ai, bj, At, Bt) do { __builtin_amdgcn_s_setprio(1); _Pragma("unroll") for (int m = 0; m < 4; ++m) _Pragma("unroll") for (int n = 0; n < 2; ++n) _Pragma("unroll") for (int k = 0; k < 2; ++k) \
;         acc[ai][bj][m][n] = __builtin_amdgcn_mfma_f32_16x16x32_bf16(Bt[n][k], At[m][k], acc[ai][bj][m][n], 0, 0, 0); __builtin_amdgcn_s_setprio(0); } while (0)
; #define PG8_WAIT_V(n) asm volatile("s_waitcnt vmcnt(" #n ")" ::: "memory")
; #define PG8_WAIT_L(n) asm volatile("s_waitcnt lgkmcnt(" #n ")" ::: "memory")
; #define PG8_BAR __builtin_amdgcn_s_barrier()
; #define PG8_SCHED __builtin_amdgcn_sched_barrier(0)
;     __device__ __forceinline__ void operator()(const f32x4 (&acc)[2][2][4][2], const Unit& u, int wr, int wc, int fr, int fq) const {
;     ...
;                     for (int n = 0; n < 2; ++n) *(f32x4*)(out + off + bj * HALF + n * 16) = res[m][bj][n] + acc[ai][bj][m][n]; }
; template <class Epi, class Sched, bool ALIGN_EPI = false, bool SP2 = false>
; __device__ __forceinline__ void gemm_phase(PG8_LAS unsigned char* lds, const Gemm g, const Sched& S, const Epi& E) {
;     ...
;             PG8_LDA(At, 1, 1); PG8_STAGE(PG8_SB(1, 0), b3, voffB); PG8_STAGE(PG8_SB(1, 1), b3 + hstep, voffB); PG8_STAGE(PG8_SA(1, 0), a3, voffA);
;             PG8_WAIT_V(8); PG8_WAIT_L(0); PG8_BAR; PG8_MMA(1, 0, At, B0); PG8_MMA(1, 1, At, B1); PG8_BAR; PG8_SCHED;
	s_add_i32 s34, s50, s30
	v_lshl_add_u64 v[144:145], v[144:145], 0, s[4:5]
	s_mov_b32 m0, s34
	ds_read_b128 v[180:183], v151 offset:49152
	ds_read_b128 v[184:187], v151 offset:50176
	ds_read_b128 v[188:191], v151 offset:51200
	ds_read_b128 v[192:195], v151 offset:52224
	ds_read_b128 v[196:199], v151 offset:53248
	ds_read_b128 v[200:203], v151 offset:54272
	ds_read_b128 v[204:207], v151 offset:55296
	ds_read_b128 v[208:211], v151 offset:56320
	global_load_lds_dwordx4 v[144:145], off
	s_add_i32 m0, s34, 0x2000
	s_add_u32 s28, s28, 0x80080
	v_lshl_add_u64 v[144:145], v[212:213], 0, s[4:5]
	s_addc_u32 s29, s29, 0
	s_add_i32 s34, s51, s30
	global_load_lds_dwordx4 v[144:145], off
	v_lshl_add_u64 v[144:145], s[28:29], 0, v[128:129]
	s_mov_b32 m0, s34
	s_nop 0
	global_load_lds_dwordx4 v[144:145], off
	v_lshl_add_u64 v[144:145], s[28:29], 0, v[130:131]
	s_add_i32 m0, s34, 0x2000
	s_nop 0
	global_load_lds_dwordx4 v[144:145], off
	v_lshl_add_u64 v[144:145], v[214:215], 0, s[4:5]
	s_mov_b32 m0, s41
	s_nop 0
	global_load_lds_dwordx4 v[144:145], off
	v_lshl_add_u64 v[144:145], v[216:217], 0, s[4:5]
	s_mov_b32 m0, s42
	s_nop 0
	global_load_lds_dwordx4 v[144:145], off
	s_waitcnt vmcnt(8)
	s_waitcnt lgkmcnt(0)
	s_barrier
	s_setprio 1
	s_waitcnt lgkmcnt(0)
	v_mfma_f32_16x16x32_bf16 v[60:63], v[140:143], v[180:183], v[60:63]
	v_mfma_f32_16x16x32_bf16 v[60:63], v[152:155], v[184:187], v[60:63]
	v_mfma_f32_16x16x32_bf16 v[52:55], v[152:155], v[192:195], v[52:55]
	v_mfma_f32_16x16x32_bf16 v[52:55], v[140:143], v[188:191], v[52:55]
	v_mfma_f32_16x16x32_bf16 v[44:47], v[140:143], v[196:199], v[44:47]
	v_mfma_f32_16x16x32_bf16 v[44:47], v[152:155], v[200:203], v[44:47]
	v_mfma_f32_16x16x32_bf16 v[28:31], v[152:155], v[208:211], v[28:31]
	v_mfma_f32_16x16x32_bf16 v[28:31], v[140:143], v[204:207], v[28:31]
	v_mfma_f32_16x16x32_bf16 v[16:19], v[156:159], v[204:207], v[16:19]
	v_mfma_f32_16x16x32_bf16 v[16:19], v[160:163], v[208:211], v[16:19]
	v_mfma_f32_16x16x32_bf16 v[36:39], v[160:163], v[200:203], v[36:39]
	v_mfma_f32_16x16x32_bf16 v[36:39], v[156:159], v[196:199], v[36:39]
	v_mfma_f32_16x16x32_bf16 v[48:51], v[156:159], v[188:191], v[48:51]
	v_mfma_f32_16x16x32_bf16 v[48:51], v[160:163], v[192:195], v[48:51]
	v_mfma_f32_16x16x32_bf16 v[56:59], v[160:163], v[184:187], v[56:59]
	v_mfma_f32_16x16x32_bf16 v[56:59], v[156:159], v[180:183], v[56:59]
	s_setprio 0
	s_setprio 1
	v_mfma_f32_16x16x32_bf16 v[40:43], v[164:167], v[180:183], v[40:43]
	v_mfma_f32_16x16x32_bf16 v[40:43], v[168:171], v[184:187], v[40:43]
	v_mfma_f32_16x16x32_bf16 v[24:27], v[168:171], v[192:195], v[24:27]
	v_mfma_f32_16x16x32_bf16 v[24:27], v[164:167], v[188:191], v[24:27]
	v_mfma_f32_16x16x32_bf16 v[12:15], v[164:167], v[196:199], v[12:15]
	v_mfma_f32_16x16x32_bf16 v[12:15], v[168:171], v[200:203], v[12:15]
	v_mfma_f32_16x16x32_bf16 v[4:7], v[168:171], v[208:211], v[4:7]
	v_mfma_f32_16x16x32_bf16 v[4:7], v[164:167], v[204:207], v[4:7]
	v_mfma_f32_16x16x32_bf16 v[0:3], v[172:175], v[204:207], v[0:3]
	v_mfma_f32_16x16x32_bf16 v[0:3], v[176:179], v[208:211], v[0:3]
	v_mfma_f32_16x16x32_bf16 v[8:11], v[176:179], v[200:203], v[8:11]
	v_mfma_f32_16x16x32_bf16 v[8:11], v[172:175], v[196:199], v[8:11]
	v_mfma_f32_16x16x32_bf16 v[20:23], v[172:175], v[188:191], v[20:23]
	v_mfma_f32_16x16x32_bf16 v[20:23], v[176:179], v[192:195], v[20:23]
	v_mfma_f32_16x16x32_bf16 v[32:35], v[176:179], v[184:187], v[32:35]
	v_mfma_f32_16x16x32_bf16 v[32:35], v[172:175], v[180:183], v[32:35]
	s_setprio 0
	s_barrier
	s_add_i32 s49, s49, 2
	s_add_u32 s26, s26, 0x100
	s_addc_u32 s27, s27, 0
	s_add_u32 s47, s47, 0x100
	s_addc_u32 s48, s48, 0
	s_cmp_gt_u32 s49, 29
	s_cbranch_scc0 .Lp3_k2
	s_branch .Lp3_k2_exit
.Lp3_epi_stream:
	s_waitcnt vmcnt(0)
	s_nop 7
	s_nop 7
	v_pk_add_f32 v[4:5], v[4:5], v[240:241]
	v_pk_add_f32 v[6:7], v[6:7], v[242:243]
	v_pk_add_f32 v[0:1], v[0:1], v[244:245]
	v_pk_add_f32 v[2:3], v[2:3], v[246:247]
	s_nop 1
	s_branch .Lp3_epi_first
